# layer-1 weight transposes moved from prep into the idle tail of layer-0 FFN-up (CUs without a 7th unit)
# speedup vs baseline: 1.0227x; 1.0027x over previous
; __device__ __forceinline__ void prep_phase(const Params& p, LAS unsigned char* lds) {
;     ...
;         for (int it = gw; it < 2 * I_L; it += NGW) {
;             const int l = it / I_L; int r = it % I_L;
;             if (r < I_IN) { const int kb = r / 72, nb = r % 72; if (nb >= 48 && nb < 56) continue;
;                 transpose_item(p.w_in + (size_t)l * DM * INW_SRC, INW_SRC, DM, (bf16_t*)(ws + WS_WIN) + (size_t)l * INW * DM, 1, scr, kb, nb, lane); continue; }
;             r -= I_IN;
;             if (r < I_OUT) { transpose_item(p.w_out + (size_t)l * DM * DM, DM, DM, (bf16_t*)(ws + WS_WOUT) + (size_t)l * DM * DM, 0, scr, r / 32, r % 32, lane); continue; }
;             r -= I_OUT;
;             if (r < I_F1) { transpose_item(p.w_ffn1 + (size_t)l * DM * DFF, DFF, DM, (bf16_t*)(ws + WS_W13) + (size_t)l * N13 * DM, 2, scr, r / 88, r % 88, lane); continue; }
;             r -= I_F1;
;             if (r < I_F1) { transpose_item(p.w_ffn3 + (size_t)l * DM * DFF, DFF, DM, (bf16_t*)(ws + WS_W13) + (size_t)l * N13 * DM, 3, scr, r / 88, r % 88, lane); continue; }
;             r -= I_F1;
;             transpose_item(p.w_ffn2 + (size_t)l * DFF * DM, DM, DFF, (bf16_t*)(ws + WS_W2) + (size_t)l * DM * DFF, 0, scr, r / 32, r % 32, lane);
;         }
.LBB0_33:
	s_or_b64 exec, exec, s[14:15]
	v_add_u32_e32 v33, s80, v33
	s_movk_i32 s12, 0x16ff
	v_cmp_lt_i32_e32 vcc, s12, v33
	s_or_b64 s[10:11], vcc, s[10:11]
	s_andn2_b64 exec, exec, s[10:11]
	s_cbranch_execz .LBB0_76

; #define LAS __attribute__((address_space(3)))
; __device__ __forceinline__ int fresh_tid() { int t = threadIdx.x; asm volatile("" : "+v"(t)); return t; }
; __device__ __forceinline__ void prep_phase(const Params& p, LAS unsigned char* lds) {
;     const int tid = fresh_tid(), lane = tid & 63, wave = tid >> 6, G = gridDim.x;
;     const int gw = blockIdx.x * 8 + wave, NGW = G * 8;
;     const int gt = blockIdx.x * 512 + tid, NGT = G * 512;
;     unsigned char* ws = p.ws;
;     LAS float* tab = (LAS float*)(lds + 73728);
;     LAS float* t64c = tab + 2048; LAS float* t64s = t64c + 64;
;     for (int m = tid; m < 2048; m += 512) tab[m] = cospif((float)m * (1.f / 1024.f));
;     if (tid < 64) { t64c[tid] = cospif((float)tid * (1.f / 32.f)); t64s[tid] = sinpif((float)tid * (1.f / 32.f)); }
;     __syncthreads();
;     if (gt < 1024) { const int pos = gt >> 4, f = gt & 15; const float inv = powf(10000.f, -(float)f / 16.f); const float ang = (float)pos * inv;
;         float* rope = (float*)(ws + WS_ROPE); rope[gt] = cosf(ang); rope[1024 + gt] = sinf(ang); }
;     {
;         LAS float* scr = (LAS float*)(lds + wave * 8448);
;         constexpr int I_IN = 16 * 72, I_OUT = 16 * 32, I_F1 = 16 * 88, I_F2 = 44 * 32, I_L = I_IN + I_OUT + 2 * I_F1 + I_F2;
;         for (int it = gw; it < 2 * I_L; it += NGW) {
.LBB0_1211:
	s_cmp_lg_u32 s72, 0
	s_cbranch_scc1 .Lt_skip
	s_cmp_lt_u32 s2, 48
	s_cbranch_scc1 .Lt_skip
	v_writelane_b32 v200, s3, 0
	v_writelane_b32 v200, s4, 1
	v_writelane_b32 v200, s5, 2
	v_writelane_b32 v200, s12, 3
	v_writelane_b32 v200, s13, 4
	v_writelane_b32 v200, s14, 5
	v_writelane_b32 v200, s15, 6
	v_writelane_b32 v200, s16, 7
	v_writelane_b32 v200, s17, 8
	v_writelane_b32 v200, s18, 9
	v_writelane_b32 v200, s19, 10
	v_writelane_b32 v200, s21, 11
	v_writelane_b32 v200, s22, 12
	v_writelane_b32 v200, s23, 13
	v_writelane_b32 v200, s26, 14
	v_writelane_b32 v200, s27, 15
	v_writelane_b32 v200, s28, 16
	v_writelane_b32 v200, s29, 17
	v_writelane_b32 v200, s33, 18
	v_writelane_b32 v200, s34, 19
	v_writelane_b32 v200, s35, 20
	v_writelane_b32 v200, s36, 21
	v_writelane_b32 v200, s37, 22
	v_writelane_b32 v200, s43, 23
	v_writelane_b32 v200, s44, 24
	v_writelane_b32 v200, s45, 25
	v_writelane_b32 v200, s46, 26
	v_writelane_b32 v200, s47, 27
	v_writelane_b32 v200, s48, 28
	v_writelane_b32 v200, s49, 29
	v_writelane_b32 v200, s80, 30
	v_writelane_b32 v200, vcc_lo, 31
	v_writelane_b32 v200, vcc_hi, 32
	v_mov_b32_e32 v66, v192
	v_lshrrev_b32_e32 v11, 6, v66
	v_and_b32_e32 v67, 63, v66
	v_lshlrev_b32_e32 v81, 2, v67
	s_sub_u32 s0, s2, 48
	s_lshl_b32 s0, s0, 3
	v_add_u32_e32 v80, s0, v11
	v_add_u32_e32 v80, 0x1700, v80
	s_movk_i32 s80, 0x680
	s_mov_b64 exec, -1

; #define LAS __attribute__((address_space(3)))
; __device__ __forceinline__ unsigned cvt_pk_bf16(float lo, float hi) { unsigned r; asm("v_cvt_pk_bf16_f32 %0, %1, %2" : "=v"(r) : "v"(lo), "v"(hi)); return r; }
; __device__ __forceinline__ void transpose_item(const float* W, int ldw, int K, bf16_t* WT, int mode, LAS float* scr, int kb, int nb, int lane) {
;     const int k0 = 64 * kb, n0 = 32 * nb;
; #pragma unroll 8
;     for (int i = 0; i < 32; ++i) { const int kk = 2 * i + (lane >> 5); scr[kk * 33 + (lane & 31)] = W[(size_t)(k0 + kk) * ldw + n0 + (lane & 31)]; }
;     asm volatile("s_waitcnt lgkmcnt(0)" ::: "memory");
;     const int c = lane & 7;
; #pragma unroll
;     for (int j = 0; j < 4; ++j) { const int n = (lane >> 3) + 8 * j; const LAS float* s = scr + (8 * c) * 33 + n;
;         u32x4 o; o.x = cvt_pk_bf16(s[0 * 33], s[1 * 33]); o.y = cvt_pk_bf16(s[2 * 33], s[3 * 33]); o.z = cvt_pk_bf16(s[4 * 33], s[5 * 33]); o.w = cvt_pk_bf16(s[6 * 33], s[7 * 33]);
;         *(u32x4*)(WT + (size_t)drow_map(mode, n0 + n) * K + k0 + 8 * c) = o; }
; __device__ __forceinline__ void prep_phase(const Params& p, LAS unsigned char* lds) {
;     ...
;         LAS float* scr = (LAS float*)(lds + wave * 8448);
;         constexpr int I_IN = 16 * 72, I_OUT = 16 * 32, I_F1 = 16 * 88, I_F2 = 44 * 32, I_L = I_IN + I_OUT + 2 * I_F1 + I_F2;
;         for (int it = gw; it < 2 * I_L; it += NGW) {
	v_readlane_b32 s4, v252, 0
	v_readlane_b32 s8, v252, 4
	v_readlane_b32 s5, v252, 1
	v_readlane_b32 s9, v252, 5
	s_add_u32 s4, s8, 0x2400000
	v_readlane_b32 s6, v252, 2
	s_addc_u32 s5, s9, 0
	s_movk_i32 s3, 0x2100
	v_readlane_b32 s7, v252, 3
	v_lshlrev_b32_e32 v3, 3, v67
	s_add_u32 s6, s8, 0xe00000
	v_mul_lo_u32 v1, v11, s3
	v_lshrrev_b32_e32 v13, 3, v67
	v_and_b32_e32 v12, 56, v3
	s_addc_u32 s7, s9, 0
	v_add_u32_e32 v1, 0, v1
	v_readlane_b32 s10, v252, 6
	v_readlane_b32 s11, v252, 7
	v_lshrrev_b32_e32 v6, 5, v67
	v_and_b32_e32 v2, 31, v66
	v_mul_u32_u24_e32 v3, 0x84, v12
	v_lshlrev_b32_e32 v4, 2, v13
	s_add_u32 s8, s8, 0xa00000
	v_mov_b32_e32 v9, 0
	v_lshl_add_u32 v10, v2, 2, v1
	s_movk_i32 s3, 0x84
	v_add3_u32 v24, v1, v3, v4
	v_or_b32_e32 v25, 8, v13
	v_or_b32_e32 v26, 16, v13
	v_or_b32_e32 v27, 24, v13
	s_movk_i32 s22, 0x80
	v_and_b32_e32 v28, 0x80, v81
	s_addc_u32 s9, s9, 0
	v_bfe_u32 v29, v67, 3, 2
	v_mov_b32_e32 v1, v6
	s_mov_b64 s[10:11], 0
	s_movk_i32 s23, 0xffc0
	s_mov_b32 s24, 0xffc0
	s_movk_i32 s25, 0x2c00
	s_movk_i32 s26, 0x63
	s_movk_i32 s27, 0x2400
	s_movk_i32 s28, 0x3ff
	s_movk_i32 s29, 0x700
	v_lshlrev_b32_e32 v14, 2, v2
	v_mov_b32_e32 v30, 1
	v_mov_b32_e32 v31, 6
	v_mov_b32_e32 v32, 5
	v_mov_b32_e32 v33, v80
	s_branch .Lt_34

; __device__ __forceinline__ void prep_phase(const Params& p, LAS unsigned char* lds) {
;     ...
;         for (int it = gw; it < 2 * I_L; it += NGW) {
;             const int l = it / I_L; int r = it % I_L;
;             if (r < I_IN) { const int kb = r / 72, nb = r % 72; if (nb >= 48 && nb < 56) continue;
;                 transpose_item(p.w_in + (size_t)l * DM * INW_SRC, INW_SRC, DM, (bf16_t*)(ws + WS_WIN) + (size_t)l * INW * DM, 1, scr, kb, nb, lane); continue; }
.Lt_34:
	s_mov_b32 s12, 0xb21642c9
	v_mul_hi_i32 v2, v33, s12
	v_add_u32_e32 v2, v2, v33
	v_lshrrev_b32_e32 v3, 31, v2
	v_ashrrev_i32_e32 v2, 12, v2
	v_add_u32_e32 v16, v2, v3
	v_mul_i32_i24_e32 v2, 0x1700, v16
	v_sub_u32_e32 v5, v33, v2
	s_movk_i32 s12, 0x47f
	v_cmp_lt_i32_e32 vcc, s12, v5
	s_and_saveexec_b64 s[12:13], vcc
	s_xor_b64 s[14:15], exec, s[12:13]
	s_cbranch_execz .Lt_56

; __device__ __forceinline__ void prep_phase(const Params& p, LAS unsigned char* lds) {
;     ...
;         for (int it = gw; it < 2 * I_L; it += NGW) {
;             const int l = it / I_L; int r = it % I_L;
;             if (r < I_IN) { const int kb = r / 72, nb = r % 72; if (nb >= 48 && nb < 56) continue;
;                 transpose_item(p.w_in + (size_t)l * DM * INW_SRC, INW_SRC, DM, (bf16_t*)(ws + WS_WIN) + (size_t)l * INW * DM, 1, scr, kb, nb, lane); continue; }
;             r -= I_IN;
;             if (r < I_OUT) { transpose_item(p.w_out + (size_t)l * DM * DM, DM, DM, (bf16_t*)(ws + WS_WOUT) + (size_t)l * DM * DM, 0, scr, r / 32, r % 32, lane); continue; }
;             r -= I_OUT;
;             if (r < I_F1) { transpose_item(p.w_ffn1 + (size_t)l * DM * DFF, DFF, DM, (bf16_t*)(ws + WS_W13) + (size_t)l * N13 * DM, 2, scr, r / 88, r % 88, lane); continue; }
	s_movk_i32 s12, 0x67f
	v_cmp_lt_u32_e32 vcc, s12, v5
	v_ashrrev_i32_e32 v17, 31, v16
	s_and_saveexec_b64 s[12:13], vcc
	s_xor_b64 s[16:17], exec, s[12:13]
	s_cbranch_execz .Lt_51

; __device__ __forceinline__ void prep_phase(const Params& p, LAS unsigned char* lds) {
;     ...
;             r -= I_OUT;
;             if (r < I_F1) { transpose_item(p.w_ffn1 + (size_t)l * DM * DFF, DFF, DM, (bf16_t*)(ws + WS_W13) + (size_t)l * N13 * DM, 2, scr, r / 88, r % 88, lane); continue; }
;             r -= I_F1;
;             if (r < I_F1) { transpose_item(p.w_ffn3 + (size_t)l * DM * DFF, DFF, DM, (bf16_t*)(ws + WS_W13) + (size_t)l * N13 * DM, 3, scr, r / 88, r % 88, lane); continue; }
	s_movk_i32 s12, 0xbff
	v_cmp_lt_u32_e32 vcc, s12, v5
	s_mov_b32 s12, 0xb00000
	v_mad_i64_i32 v[2:3], s[12:13], v16, s12, 0
	s_and_saveexec_b64 s[12:13], vcc
	s_xor_b64 s[18:19], exec, s[12:13]
	s_cbranch_execz .Lt_46

; __device__ __forceinline__ void prep_phase(const Params& p, LAS unsigned char* lds) {
;     ...
;             r -= I_F1;
;             if (r < I_F1) { transpose_item(p.w_ffn3 + (size_t)l * DM * DFF, DFF, DM, (bf16_t*)(ws + WS_W13) + (size_t)l * N13 * DM, 3, scr, r / 88, r % 88, lane); continue; }
;             r -= I_F1;
;             transpose_item(p.w_ffn2 + (size_t)l * DFF * DM, DM, DFF, (bf16_t*)(ws + WS_W2) + (size_t)l * DM * DFF, 0, scr, r / 32, r % 32, lane);
	s_movk_i32 s12, 0x117f
	v_cmp_lt_u32_e32 vcc, s12, v5
	s_and_saveexec_b64 s[12:13], vcc
	s_xor_b64 s[20:21], exec, s[12:13]
	s_cbranch_execz .Lt_41

; #define LAS __attribute__((address_space(3)))
; __device__ __forceinline__ void transpose_item(const float* W, int ldw, int K, bf16_t* WT, int mode, LAS float* scr, int kb, int nb, int lane) {
;     const int k0 = 64 * kb, n0 = 32 * nb;
; #pragma unroll 8
;     for (int i = 0; i < 32; ++i) { const int kk = 2 * i + (lane >> 5); scr[kk * 33 + (lane & 31)] = W[(size_t)(k0 + kk) * ldw + n0 + (lane & 31)]; }
; __device__ __forceinline__ void prep_phase(const Params& p, LAS unsigned char* lds) {
;     ...
;             transpose_item(p.w_ffn2 + (size_t)l * DFF * DM, DM, DFF, (bf16_t*)(ws + WS_W2) + (size_t)l * DM * DFF, 0, scr, r / 32, r % 32, lane);
	v_readlane_b32 s36, v252, 48
	v_readlane_b32 s50, v252, 62
	v_readlane_b32 s51, v252, 63
	v_mov_b32_e32 v15, v9
	s_mov_b32 s30, 1
	v_lshl_add_u64 v[18:19], s[50:51], 0, v[2:3]
	v_lshlrev_b32_e32 v3, 5, v5
	v_lshlrev_b32_e32 v2, 1, v5
	v_and_b32_e32 v7, 0x3e0, v3
	v_and_b32_e32 v2, 0x7fffffc0, v2
	v_lshlrev_b32_e32 v8, 2, v7
	v_add_u32_e32 v2, 0xffffdd00, v2
	v_lshl_add_u64 v[4:5], v[18:19], 0, v[8:9]
	v_lshl_add_u64 v[4:5], v[4:5], 0, v[14:15]
	v_or_b32_e32 v3, v1, v2
	v_or_b32_e32 v8, v6, v2
	s_mov_b32 s31, 0
	s_mov_b32 s33, 32
	v_readlane_b32 s37, v252, 49
	v_readlane_b32 s38, v252, 50
	v_readlane_b32 s39, v252, 51
	v_readlane_b32 s40, v252, 52
	v_readlane_b32 s41, v252, 53
	v_readlane_b32 s42, v252, 54
	v_readlane_b32 s43, v252, 55
	v_readlane_b32 s44, v252, 56
	v_readlane_b32 s45, v252, 57
	v_readlane_b32 s46, v252, 58
	v_readlane_b32 s47, v252, 59
	v_readlane_b32 s48, v252, 60
	v_readlane_b32 s49, v252, 61
.Lt_39:
	s_lshl_b32 s34, s30, 1
	s_lshl_b32 s35, s31, 1
	v_or_b32_e32 v20, s35, v8
	s_add_i32 s36, s34, 4
	s_add_i32 s37, s35, 4
	s_add_i32 s12, s34, 8
	s_add_i32 s13, s35, 8
	s_add_i32 s38, s34, 12
	s_add_i32 s39, s35, 12
	s_add_i32 s40, s34, 16
	s_add_i32 s41, s35, 16
	s_add_i32 s42, s34, 20
	s_add_i32 s43, s35, 20
	s_add_i32 s44, s34, 24
	s_add_i32 s45, s35, 24
	s_add_i32 s46, s34, 28
	s_add_i32 s47, s35, 28
	v_or_b32_e32 v18, s34, v3
	v_ashrrev_i32_e32 v21, 31, v20
	v_or_b32_e32 v22, s36, v3
	v_or_b32_e32 v34, s37, v8
	v_or_b32_e32 v36, s12, v3
	v_or_b32_e32 v38, s13, v8
	v_or_b32_e32 v40, s38, v3
	v_or_b32_e32 v42, s39, v8
	v_or_b32_e32 v44, s40, v3
	v_or_b32_e32 v46, s41, v8
	v_or_b32_e32 v48, s42, v3
	v_or_b32_e32 v50, s43, v8
	v_or_b32_e32 v52, s44, v3
	v_or_b32_e32 v54, s45, v8
	v_or_b32_e32 v56, s46, v3
	v_or_b32_e32 v58, s47, v8
	v_ashrrev_i32_e32 v19, 31, v18
	v_lshlrev_b64 v[20:21], 12, v[20:21]
	v_ashrrev_i32_e32 v35, 31, v34
	v_ashrrev_i32_e32 v23, 31, v22
	v_ashrrev_i32_e32 v39, 31, v38
	v_ashrrev_i32_e32 v37, 31, v36
	v_ashrrev_i32_e32 v43, 31, v42
	v_ashrrev_i32_e32 v41, 31, v40
	v_ashrrev_i32_e32 v47, 31, v46
	v_ashrrev_i32_e32 v45, 31, v44
	v_ashrrev_i32_e32 v51, 31, v50
	v_ashrrev_i32_e32 v49, 31, v48
	v_ashrrev_i32_e32 v55, 31, v54
	v_ashrrev_i32_e32 v53, 31, v52
	v_ashrrev_i32_e32 v59, 31, v58
	v_ashrrev_i32_e32 v57, 31, v56
	v_lshlrev_b64 v[18:19], 12, v[18:19]
	v_lshl_add_u64 v[20:21], v[4:5], 0, v[20:21]
	v_lshlrev_b64 v[22:23], 12, v[22:23]
	v_lshlrev_b64 v[34:35], 12, v[34:35]
	v_lshlrev_b64 v[36:37], 12, v[36:37]
	v_lshlrev_b64 v[38:39], 12, v[38:39]
	v_lshlrev_b64 v[40:41], 12, v[40:41]
	v_lshlrev_b64 v[42:43], 12, v[42:43]
	v_lshlrev_b64 v[44:45], 12, v[44:45]
	v_lshlrev_b64 v[46:47], 12, v[46:47]
	v_lshlrev_b64 v[48:49], 12, v[48:49]
	v_lshlrev_b64 v[50:51], 12, v[50:51]
	v_lshlrev_b64 v[52:53], 12, v[52:53]
	v_lshlrev_b64 v[54:55], 12, v[54:55]
	v_lshlrev_b64 v[56:57], 12, v[56:57]
	v_lshlrev_b64 v[58:59], 12, v[58:59]
	v_lshl_add_u64 v[18:19], v[4:5], 0, v[18:19]
	v_lshl_add_u64 v[34:35], v[4:5], 0, v[34:35]
	v_lshl_add_u64 v[22:23], v[4:5], 0, v[22:23]
	v_lshl_add_u64 v[38:39], v[4:5], 0, v[38:39]
	v_lshl_add_u64 v[36:37], v[4:5], 0, v[36:37]
	v_lshl_add_u64 v[42:43], v[4:5], 0, v[42:43]
	v_lshl_add_u64 v[40:41], v[4:5], 0, v[40:41]
	v_lshl_add_u64 v[46:47], v[4:5], 0, v[46:47]
	v_lshl_add_u64 v[44:45], v[4:5], 0, v[44:45]
	v_lshl_add_u64 v[50:51], v[4:5], 0, v[50:51]
	v_lshl_add_u64 v[48:49], v[4:5], 0, v[48:49]
	v_lshl_add_u64 v[54:55], v[4:5], 0, v[54:55]
	v_lshl_add_u64 v[52:53], v[4:5], 0, v[52:53]
	v_lshl_add_u64 v[58:59], v[4:5], 0, v[58:59]
	v_lshl_add_u64 v[56:57], v[4:5], 0, v[56:57]
	global_load_dword v15, v[20:21], off
	global_load_dword v17, v[18:19], off
	global_load_dword v60, v[34:35], off
	global_load_dword v61, v[22:23], off
	global_load_dword v62, v[38:39], off
	global_load_dword v63, v[36:37], off
	global_load_dword v64, v[42:43], off
	global_load_dword v65, v[40:41], off
	global_load_dword v69, v[46:47], off
	global_load_dword v70, v[44:45], off
	global_load_dword v71, v[50:51], off
	global_load_dword v72, v[48:49], off
	global_load_dword v73, v[54:55], off
	global_load_dword v74, v[52:53], off
	global_load_dword v75, v[58:59], off
	global_load_dword v76, v[56:57], off
	v_or_b32_e32 v20, s34, v1
	v_or_b32_e32 v18, s35, v6
	s_add_i32 s31, s31, 16
	s_add_i32 s30, s30, 16
	s_add_i32 s33, s33, -16
	v_mad_u64_u32 v[18:19], s[34:35], v18, s3, v[10:11]
	v_mad_u64_u32 v[20:21], s[34:35], v20, s3, v[10:11]
	v_or_b32_e32 v19, s36, v1
	v_or_b32_e32 v21, s37, v6
	v_or_b32_e32 v38, s12, v1
	v_or_b32_e32 v36, s13, v6
	v_or_b32_e32 v42, s38, v1
	v_or_b32_e32 v40, s39, v6
	v_or_b32_e32 v46, s40, v1
	v_or_b32_e32 v44, s41, v6
	v_or_b32_e32 v50, s42, v1
	v_or_b32_e32 v48, s43, v6
	v_or_b32_e32 v54, s44, v1
	v_or_b32_e32 v52, s45, v6
	v_or_b32_e32 v58, s46, v1
	v_or_b32_e32 v56, s47, v6
	s_cmp_lg_u32 s33, 0
	v_mad_u64_u32 v[22:23], s[12:13], v21, s3, v[10:11]
	v_mad_u64_u32 v[34:35], s[12:13], v19, s3, v[10:11]
	v_mad_u64_u32 v[36:37], s[12:13], v36, s3, v[10:11]
	v_mad_u64_u32 v[38:39], s[12:13], v38, s3, v[10:11]
	v_mad_u64_u32 v[40:41], s[12:13], v40, s3, v[10:11]
	v_mad_u64_u32 v[42:43], s[12:13], v42, s3, v[10:11]
	v_mad_u64_u32 v[44:45], s[12:13], v44, s3, v[10:11]
	v_mad_u64_u32 v[46:47], s[12:13], v46, s3, v[10:11]
	v_mad_u64_u32 v[48:49], s[12:13], v48, s3, v[10:11]
	v_mad_u64_u32 v[50:51], s[12:13], v50, s3, v[10:11]
	v_mad_u64_u32 v[52:53], s[12:13], v52, s3, v[10:11]
	v_mad_u64_u32 v[54:55], s[12:13], v54, s3, v[10:11]
	v_mad_u64_u32 v[56:57], s[12:13], v56, s3, v[10:11]
	v_mad_u64_u32 v[58:59], s[12:13], v58, s3, v[10:11]
	s_waitcnt vmcnt(15)
	ds_write_b32 v18, v15
	s_waitcnt vmcnt(14)
	ds_write_b32 v20, v17
	s_waitcnt vmcnt(13)
	ds_write_b32 v22, v60
	s_waitcnt vmcnt(12)
	ds_write_b32 v34, v61
	s_waitcnt vmcnt(11)
	ds_write_b32 v36, v62
	s_waitcnt vmcnt(10)
	ds_write_b32 v38, v63
	s_waitcnt vmcnt(9)
	ds_write_b32 v40, v64
	s_waitcnt vmcnt(8)
	ds_write_b32 v42, v65
	s_waitcnt vmcnt(7)
	ds_write_b32 v44, v69
	s_waitcnt vmcnt(6)
	ds_write_b32 v46, v70
	s_waitcnt vmcnt(5)
	ds_write_b32 v48, v71
	s_waitcnt vmcnt(4)
	ds_write_b32 v50, v72
	s_waitcnt vmcnt(3)
	ds_write_b32 v52, v73
	s_waitcnt vmcnt(2)
	ds_write_b32 v54, v74
	s_waitcnt vmcnt(1)
	ds_write_b32 v56, v75
	s_waitcnt vmcnt(0)
	ds_write_b32 v58, v76
	s_cbranch_scc1 .Lt_39

; #define LAS __attribute__((address_space(3)))
; __device__ __forceinline__ unsigned cvt_pk_bf16(float lo, float hi) { unsigned r; asm("v_cvt_pk_bf16_f32 %0, %1, %2" : "=v"(r) : "v"(lo), "v"(hi)); return r; }
; __device__ __forceinline__ void transpose_item(const float* W, int ldw, int K, bf16_t* WT, int mode, LAS float* scr, int kb, int nb, int lane) {
;     ...
;     asm volatile("s_waitcnt lgkmcnt(0)" ::: "memory");
;     const int c = lane & 7;
; #pragma unroll
;     for (int j = 0; j < 4; ++j) { const int n = (lane >> 3) + 8 * j; const LAS float* s = scr + (8 * c) * 33 + n;
;         u32x4 o; o.x = cvt_pk_bf16(s[0 * 33], s[1 * 33]); o.y = cvt_pk_bf16(s[2 * 33], s[3 * 33]); o.z = cvt_pk_bf16(s[4 * 33], s[5 * 33]); o.w = cvt_pk_bf16(s[6 * 33], s[7 * 33]);
;         *(u32x4*)(WT + (size_t)drow_map(mode, n0 + n) * K + k0 + 8 * c) = o; }
	v_mul_hi_i32_i24_e32 v5, 0x580000, v16
	v_mul_i32_i24_e32 v4, 0x580000, v16
	v_lshl_add_u64 v[4:5], s[4:5], 0, v[4:5]
	s_waitcnt lgkmcnt(0)
	v_mov_b32_e32 v3, v9
	v_lshl_add_u64 v[2:3], v[2:3], 1, v[4:5]
	v_lshlrev_b32_e32 v8, 1, v12
	ds_read2_b32 v[16:17], v24 offset0:33 offset1:41
	ds_read2_b32 v[18:19], v24 offset1:8
	ds_read2_b32 v[20:21], v24 offset0:66 offset1:74
	ds_read2_b32 v[22:23], v24 offset0:99 offset1:107
	ds_read2_b32 v[34:35], v24 offset0:132 offset1:140
	ds_read2_b32 v[36:37], v24 offset0:165 offset1:173
	ds_read2_b32 v[38:39], v24 offset0:198 offset1:206
	ds_read2_b32 v[40:41], v24 offset0:231 offset1:239
	v_lshl_add_u64 v[42:43], v[2:3], 0, v[8:9]
	v_or_b32_e32 v8, v7, v13
	v_mul_u32_u24_e32 v8, 0xb00, v8
	v_lshlrev_b32_e32 v8, 1, v8
	v_lshl_add_u64 v[44:45], v[42:43], 0, v[8:9]
	v_or_b32_e32 v8, v7, v25
	s_waitcnt lgkmcnt(6)
	v_cvt_pk_bf16_f32 v2, v18, v16
	s_waitcnt lgkmcnt(4)
	v_cvt_pk_bf16_f32 v3, v20, v22
	s_waitcnt lgkmcnt(2)
	v_cvt_pk_bf16_f32 v4, v34, v36
	s_waitcnt lgkmcnt(0)
	v_cvt_pk_bf16_f32 v5, v38, v40
	global_store_dwordx4 v[44:45], v[2:5], off
	v_mul_u32_u24_e32 v8, 0xb00, v8
	v_lshlrev_b32_e32 v8, 1, v8
	v_cvt_pk_bf16_f32 v2, v19, v17
	v_cvt_pk_bf16_f32 v3, v21, v23
	v_cvt_pk_bf16_f32 v4, v35, v37
	v_cvt_pk_bf16_f32 v5, v39, v41
	ds_read2_b32 v[18:19], v24 offset0:16 offset1:24
	ds_read2_b32 v[20:21], v24 offset0:49 offset1:57
	ds_read2_b32 v[22:23], v24 offset0:82 offset1:90
	ds_read2_b32 v[34:35], v24 offset0:115 offset1:123
	ds_read2_b32 v[36:37], v24 offset0:148 offset1:156
	ds_read2_b32 v[38:39], v24 offset0:181 offset1:189
	ds_read2_b32 v[40:41], v24 offset0:214 offset1:222
	ds_read2_b32 v[44:45], v24 offset0:247 offset1:255
	v_lshl_add_u64 v[16:17], v[42:43], 0, v[8:9]
	v_or_b32_e32 v8, v7, v26
	v_mul_u32_u24_e32 v8, 0xb00, v8
	v_or_b32_e32 v7, v7, v27
	v_lshlrev_b32_e32 v8, 1, v8
	v_mul_u32_u24_e32 v7, 0xb00, v7
	global_store_dwordx4 v[16:17], v[2:5], off
	v_lshl_add_u64 v[16:17], v[42:43], 0, v[8:9]
	v_lshlrev_b32_e32 v8, 1, v7
	s_waitcnt lgkmcnt(6)
	v_cvt_pk_bf16_f32 v2, v18, v20
	s_waitcnt lgkmcnt(4)
	v_cvt_pk_bf16_f32 v3, v22, v34
	s_waitcnt lgkmcnt(2)
	v_cvt_pk_bf16_f32 v4, v36, v38
	s_waitcnt lgkmcnt(0)
	v_cvt_pk_bf16_f32 v5, v40, v44
	global_store_dwordx4 v[16:17], v[2:5], off
	v_lshl_add_u64 v[16:17], v[42:43], 0, v[8:9]
	s_nop 0
	v_cvt_pk_bf16_f32 v2, v19, v21
	v_cvt_pk_bf16_f32 v3, v23, v35
	v_cvt_pk_bf16_f32 v4, v37, v39
	v_cvt_pk_bf16_f32 v5, v41, v45
	global_store_dwordx4 v[16:17], v[2:5], off
	s_waitcnt lgkmcnt(0)
.Lt_41:
	s_andn2_saveexec_b64 s[20:21], s[20:21]
	s_cbranch_execz .Lt_45

; #define LAS __attribute__((address_space(3)))
; __device__ __forceinline__ void transpose_item(const float* W, int ldw, int K, bf16_t* WT, int mode, LAS float* scr, int kb, int nb, int lane) {
;     const int k0 = 64 * kb, n0 = 32 * nb;
; #pragma unroll 8
;     for (int i = 0; i < 32; ++i) { const int kk = 2 * i + (lane >> 5); scr[kk * 33 + (lane & 31)] = W[(size_t)(k0 + kk) * ldw + n0 + (lane & 31)]; }
; __device__ __forceinline__ void prep_phase(const Params& p, LAS unsigned char* lds) {
;     ...
;             if (r < I_F1) { transpose_item(p.w_ffn3 + (size_t)l * DM * DFF, DFF, DM, (bf16_t*)(ws + WS_W13) + (size_t)l * N13 * DM, 3, scr, r / 88, r % 88, lane); continue; }
	v_add_u16_e32 v4, 0xf400, v5
	v_mul_u32_u24_e32 v7, 0xba2f, v4
	v_lshrrev_b32_e32 v5, 22, v7
	v_readlane_b32 s36, v252, 48
	v_mul_lo_u16_e32 v5, 0x58, v5
	v_readlane_b32 s48, v252, 60
	v_readlane_b32 s49, v252, 61
	v_sub_u16_e32 v18, v4, v5
	v_lshlrev_b32_e32 v8, 7, v18
	v_lshl_add_u64 v[20:21], s[48:49], 0, v[2:3]
	v_lshl_add_u64 v[4:5], v[20:21], 0, v[8:9]
	v_mov_b32_e32 v15, v9
	v_and_b32_sdwa v8, v7, s24 dst_sel:DWORD dst_unused:UNUSED_PAD src0_sel:WORD_1 src1_sel:DWORD
	v_readlane_b32 s37, v252, 49
	v_readlane_b32 s38, v252, 50
	v_readlane_b32 s39, v252, 51
	v_readlane_b32 s40, v252, 52
	v_readlane_b32 s41, v252, 53
	v_readlane_b32 s42, v252, 54
	v_readlane_b32 s43, v252, 55
	v_readlane_b32 s44, v252, 56
	v_readlane_b32 s45, v252, 57
	v_readlane_b32 s46, v252, 58
	v_readlane_b32 s47, v252, 59
	v_readlane_b32 s50, v252, 62
	v_readlane_b32 s51, v252, 63
	v_and_b32_sdwa v17, v7, s23 dst_sel:DWORD dst_unused:UNUSED_PAD src0_sel:WORD_1 src1_sel:DWORD
	v_lshlrev_b32_e32 v16, 5, v18
	v_lshl_add_u64 v[4:5], v[4:5], 0, v[14:15]
	v_or_b32_e32 v7, v1, v8
	v_or_b32_e32 v8, v6, v8
	s_mov_b32 s12, 1
	s_mov_b32 s13, 0
	s_mov_b32 s30, 32
.Lt_43:
	s_lshl_b32 s31, s12, 1
	s_lshl_b32 s33, s13, 1
	v_or_b32_e32 v15, s31, v7
	v_or_b32_e32 v19, s33, v8
	s_add_i32 s36, s31, 4
	s_add_i32 s37, s33, 4
	s_add_i32 s38, s31, 8
	s_add_i32 s39, s33, 8
	s_add_i32 s40, s31, 12
	s_add_i32 s41, s33, 12
	s_add_i32 s42, s31, 16
	s_add_i32 s43, s33, 16
	s_add_i32 s44, s31, 20
	s_add_i32 s45, s33, 20
	s_add_i32 s46, s31, 24
	s_add_i32 s47, s33, 24
	s_add_i32 s48, s31, 28
	s_add_i32 s49, s33, 28
	v_mad_u64_u32 v[20:21], s[34:35], v19, s25, v[4:5]
	v_mad_u64_u32 v[22:23], s[34:35], v15, s25, v[4:5]
	v_or_b32_e32 v15, s36, v7
	v_or_b32_e32 v19, s37, v8
	v_or_b32_e32 v40, s38, v7
	v_or_b32_e32 v38, s39, v8
	v_or_b32_e32 v44, s40, v7
	v_or_b32_e32 v42, s41, v8
	v_or_b32_e32 v48, s42, v7
	v_or_b32_e32 v46, s43, v8
	v_or_b32_e32 v52, s44, v7
	v_or_b32_e32 v50, s45, v8
	v_or_b32_e32 v56, s46, v7
	v_or_b32_e32 v54, s47, v8
	v_or_b32_e32 v60, s48, v7
	v_or_b32_e32 v58, s49, v8
	v_mad_u64_u32 v[34:35], s[34:35], v19, s25, v[4:5]
	v_mad_u64_u32 v[36:37], s[34:35], v15, s25, v[4:5]
	v_mad_u64_u32 v[38:39], s[34:35], v38, s25, v[4:5]
	v_mad_u64_u32 v[40:41], s[34:35], v40, s25, v[4:5]
	v_mad_u64_u32 v[42:43], s[34:35], v42, s25, v[4:5]
	v_mad_u64_u32 v[44:45], s[34:35], v44, s25, v[4:5]
	v_mad_u64_u32 v[46:47], s[34:35], v46, s25, v[4:5]
	v_mad_u64_u32 v[48:49], s[34:35], v48, s25, v[4:5]
	v_mad_u64_u32 v[50:51], s[34:35], v50, s25, v[4:5]
	v_mad_u64_u32 v[52:53], s[34:35], v52, s25, v[4:5]
	v_mad_u64_u32 v[54:55], s[34:35], v54, s25, v[4:5]
	v_mad_u64_u32 v[56:57], s[34:35], v56, s25, v[4:5]
	v_mad_u64_u32 v[58:59], s[34:35], v58, s25, v[4:5]
	v_mad_u64_u32 v[60:61], s[34:35], v60, s25, v[4:5]
	global_load_dword v15, v[20:21], off
	global_load_dword v19, v[22:23], off
	global_load_dword v62, v[34:35], off
	global_load_dword v63, v[36:37], off
	global_load_dword v64, v[38:39], off
	global_load_dword v65, v[40:41], off
	global_load_dword v69, v[42:43], off
	global_load_dword v70, v[44:45], off
	global_load_dword v71, v[46:47], off
	global_load_dword v72, v[48:49], off
	global_load_dword v73, v[50:51], off
	global_load_dword v74, v[52:53], off
	global_load_dword v75, v[54:55], off
	global_load_dword v76, v[56:57], off
	global_load_dword v77, v[58:59], off
	global_load_dword v78, v[60:61], off
	v_or_b32_e32 v22, s31, v1
	v_or_b32_e32 v20, s33, v6
	s_add_i32 s13, s13, 16
	s_add_i32 s12, s12, 16
	s_add_i32 s30, s30, -16
	v_mad_u64_u32 v[20:21], s[34:35], v20, s3, v[10:11]
	v_mad_u64_u32 v[22:23], s[34:35], v22, s3, v[10:11]
	v_or_b32_e32 v21, s36, v1
	v_or_b32_e32 v23, s37, v6
	v_or_b32_e32 v40, s38, v1
	v_or_b32_e32 v38, s39, v6
	v_or_b32_e32 v44, s40, v1
	v_or_b32_e32 v42, s41, v6
	v_or_b32_e32 v48, s42, v1
	v_or_b32_e32 v46, s43, v6
	v_or_b32_e32 v52, s44, v1
	v_or_b32_e32 v50, s45, v6
	v_or_b32_e32 v56, s46, v1
	v_or_b32_e32 v54, s47, v6
	v_or_b32_e32 v60, s48, v1
	v_or_b32_e32 v58, s49, v6
	s_cmp_lg_u32 s30, 0
	v_mad_u64_u32 v[34:35], s[34:35], v23, s3, v[10:11]
	v_mad_u64_u32 v[36:37], s[34:35], v21, s3, v[10:11]
	v_mad_u64_u32 v[38:39], s[34:35], v38, s3, v[10:11]
	v_mad_u64_u32 v[40:41], s[34:35], v40, s3, v[10:11]
	v_mad_u64_u32 v[42:43], s[34:35], v42, s3, v[10:11]
	v_mad_u64_u32 v[44:45], s[34:35], v44, s3, v[10:11]
	v_mad_u64_u32 v[46:47], s[34:35], v46, s3, v[10:11]
	v_mad_u64_u32 v[48:49], s[34:35], v48, s3, v[10:11]
	v_mad_u64_u32 v[50:51], s[34:35], v50, s3, v[10:11]
	v_mad_u64_u32 v[52:53], s[34:35], v52, s3, v[10:11]
	v_mad_u64_u32 v[54:55], s[34:35], v54, s3, v[10:11]
	v_mad_u64_u32 v[56:57], s[34:35], v56, s3, v[10:11]
	v_mad_u64_u32 v[58:59], s[34:35], v58, s3, v[10:11]
	v_mad_u64_u32 v[60:61], s[34:35], v60, s3, v[10:11]
	s_waitcnt vmcnt(15)
	ds_write_b32 v20, v15
	s_waitcnt vmcnt(14)
	ds_write_b32 v22, v19
	s_waitcnt vmcnt(13)
	ds_write_b32 v34, v62
	s_waitcnt vmcnt(12)
	ds_write_b32 v36, v63
	s_waitcnt vmcnt(11)
	ds_write_b32 v38, v64
	s_waitcnt vmcnt(10)
	ds_write_b32 v40, v65
	s_waitcnt vmcnt(9)
	ds_write_b32 v42, v69
	s_waitcnt vmcnt(8)
	ds_write_b32 v44, v70
	s_waitcnt vmcnt(7)
	ds_write_b32 v46, v71
	s_waitcnt vmcnt(6)
	ds_write_b32 v48, v72
	s_waitcnt vmcnt(5)
	ds_write_b32 v50, v73
	s_waitcnt vmcnt(4)
	ds_write_b32 v52, v74
	s_waitcnt vmcnt(3)
	ds_write_b32 v54, v75
	s_waitcnt vmcnt(2)
	ds_write_b32 v56, v76
	s_waitcnt vmcnt(1)
	ds_write_b32 v58, v77
	s_waitcnt vmcnt(0)
	ds_write_b32 v60, v78
	s_cbranch_scc1 .Lt_43

; #define LAS __attribute__((address_space(3)))
; __device__ __forceinline__ unsigned cvt_pk_bf16(float lo, float hi) { unsigned r; asm("v_cvt_pk_bf16_f32 %0, %1, %2" : "=v"(r) : "v"(lo), "v"(hi)); return r; }
; __device__ __forceinline__ int drow_map(int mode, int n) {
;     ...
;     const int r = 256 * (n >> 7) + 128 * ((n >> 2) & 1) + 32 * ((n >> 5) & 3) + 4 * ((n >> 3) & 3) + (n & 3);
;     return mode == 2 ? r : r + 16;
; __device__ __forceinline__ void transpose_item(const float* W, int ldw, int K, bf16_t* WT, int mode, LAS float* scr, int kb, int nb, int lane) {
;     ...
;     asm volatile("s_waitcnt lgkmcnt(0)" ::: "memory");
;     const int c = lane & 7;
; #pragma unroll
;     for (int j = 0; j < 4; ++j) { const int n = (lane >> 3) + 8 * j; const LAS float* s = scr + (8 * c) * 33 + n;
;         u32x4 o; o.x = cvt_pk_bf16(s[0 * 33], s[1 * 33]); o.y = cvt_pk_bf16(s[2 * 33], s[3 * 33]); o.z = cvt_pk_bf16(s[4 * 33], s[5 * 33]); o.w = cvt_pk_bf16(s[6 * 33], s[7 * 33]);
;         *(u32x4*)(WT + (size_t)drow_map(mode, n0 + n) * K + k0 + 8 * c) = o; }
	v_lshl_add_u64 v[2:3], s[6:7], 0, v[2:3]
	v_lshlrev_b32_sdwa v8, v30, v17 dst_sel:DWORD dst_unused:UNUSED_PAD src0_sel:DWORD src1_sel:WORD_0
	v_lshlrev_b32_e32 v4, 6, v18
	v_lshl_add_u64 v[2:3], v[2:3], 0, v[8:9]
	v_lshlrev_b32_e32 v8, 1, v12
	s_waitcnt lgkmcnt(0)
	v_and_b32_e32 v7, 0x1f00, v4
	v_lshl_add_u64 v[44:45], v[2:3], 0, v[8:9]
	v_bitop3_b32 v8, v16, s26, v13 bitop3:0xc8
	ds_read2_b32 v[18:19], v24 offset0:33 offset1:41
	ds_read2_b32 v[20:21], v24 offset1:8
	ds_read2_b32 v[22:23], v24 offset0:66 offset1:74
	ds_read2_b32 v[34:35], v24 offset0:99 offset1:107
	ds_read2_b32 v[36:37], v24 offset0:132 offset1:140
	ds_read2_b32 v[38:39], v24 offset0:165 offset1:173
	ds_read2_b32 v[40:41], v24 offset0:198 offset1:206
	ds_read2_b32 v[42:43], v24 offset0:231 offset1:239
	v_or3_b32 v7, v7, v8, v28
	v_lshlrev_b32_e32 v8, 11, v7
	v_lshl_add_u64 v[16:17], v[44:45], 0, v[8:9]
	s_mov_b32 s12, 0x8000
	v_add_co_u32_e32 v44, vcc, s12, v16
	s_waitcnt lgkmcnt(6)
	v_cvt_pk_bf16_f32 v2, v20, v18
	s_waitcnt lgkmcnt(4)
	v_cvt_pk_bf16_f32 v3, v22, v34
	s_waitcnt lgkmcnt(2)
	v_cvt_pk_bf16_f32 v4, v36, v38
	s_waitcnt lgkmcnt(0)
	v_cvt_pk_bf16_f32 v5, v40, v42
	v_addc_co_u32_e32 v45, vcc, 0, v17, vcc
	global_store_dwordx4 v[44:45], v[2:5], off
	s_mov_b32 s12, 0xa000
	v_add_co_u32_e32 v18, vcc, s12, v16
	v_cvt_pk_bf16_f32 v2, v21, v19
	v_cvt_pk_bf16_f32 v3, v23, v35
	v_cvt_pk_bf16_f32 v4, v37, v39
	v_cvt_pk_bf16_f32 v5, v41, v43
	ds_read2_b32 v[20:21], v24 offset0:16 offset1:24
	ds_read2_b32 v[22:23], v24 offset0:49 offset1:57
	ds_read2_b32 v[34:35], v24 offset0:82 offset1:90
	ds_read2_b32 v[36:37], v24 offset0:115 offset1:123
	ds_read2_b32 v[38:39], v24 offset0:148 offset1:156
	ds_read2_b32 v[40:41], v24 offset0:181 offset1:189
	ds_read2_b32 v[42:43], v24 offset0:214 offset1:222
	ds_read2_b32 v[44:45], v24 offset0:247 offset1:255
	v_addc_co_u32_e32 v19, vcc, 0, v17, vcc
	s_mov_b32 s12, 0xc000
	global_store_dwordx4 v[18:19], v[2:5], off
	v_add_co_u32_e32 v18, vcc, s12, v16
	s_waitcnt lgkmcnt(6)
	v_cvt_pk_bf16_f32 v2, v20, v22
	s_waitcnt lgkmcnt(4)
	v_cvt_pk_bf16_f32 v3, v34, v36
	s_waitcnt lgkmcnt(2)
	v_cvt_pk_bf16_f32 v4, v38, v40
	s_waitcnt lgkmcnt(0)
	v_cvt_pk_bf16_f32 v5, v42, v44
	v_addc_co_u32_e32 v19, vcc, 0, v17, vcc
	v_add_co_u32_e32 v16, vcc, 0xe000, v16
	global_store_dwordx4 v[18:19], v[2:5], off
	s_nop 0
	v_addc_co_u32_e32 v17, vcc, 0, v17, vcc
	v_cvt_pk_bf16_f32 v2, v21, v23
	v_cvt_pk_bf16_f32 v3, v35, v37
	v_cvt_pk_bf16_f32 v4, v39, v41
	v_cvt_pk_bf16_f32 v5, v43, v45
	global_store_dwordx4 v[16:17], v[2:5], off
	s_waitcnt lgkmcnt(0)

; __device__ __forceinline__ void prep_phase(const Params& p, LAS unsigned char* lds) {
;     ...
;             if (r < I_F1) { transpose_item(p.w_ffn1 + (size_t)l * DM * DFF, DFF, DM, (bf16_t*)(ws + WS_W13) + (size_t)l * N13 * DM, 2, scr, r / 88, r % 88, lane); continue; }
;             r -= I_F1;
;             if (r < I_F1) { transpose_item(p.w_ffn3 + (size_t)l * DM * DFF, DFF, DM, (bf16_t*)(ws + WS_W13) + (size_t)l * N13 * DM, 3, scr, r / 88, r % 88, lane); continue; }
.Lt_46:
	s_andn2_saveexec_b64 s[18:19], s[18:19]
	s_cbranch_execz .Lt_50

; #define LAS __attribute__((address_space(3)))
; __device__ __forceinline__ void transpose_item(const float* W, int ldw, int K, bf16_t* WT, int mode, LAS float* scr, int kb, int nb, int lane) {
;     const int k0 = 64 * kb, n0 = 32 * nb;
; #pragma unroll 8
;     for (int i = 0; i < 32; ++i) { const int kk = 2 * i + (lane >> 5); scr[kk * 33 + (lane & 31)] = W[(size_t)(k0 + kk) * ldw + n0 + (lane & 31)]; }
; __device__ __forceinline__ void prep_phase(const Params& p, LAS unsigned char* lds) {
;     ...
;             if (r < I_F1) { transpose_item(p.w_ffn1 + (size_t)l * DM * DFF, DFF, DM, (bf16_t*)(ws + WS_W13) + (size_t)l * N13 * DM, 2, scr, r / 88, r % 88, lane); continue; }
	v_add_u16_e32 v4, 0xf980, v5
	v_mul_u32_u24_e32 v7, 0xba2f, v4
	v_lshrrev_b32_e32 v5, 22, v7
	v_readlane_b32 s36, v252, 48
	v_mul_lo_u16_e32 v5, 0x58, v5
	v_readlane_b32 s46, v252, 58
	v_readlane_b32 s47, v252, 59
	v_sub_u16_e32 v18, v4, v5
	v_lshlrev_b32_e32 v8, 7, v18
	v_lshl_add_u64 v[20:21], s[46:47], 0, v[2:3]
	v_lshl_add_u64 v[4:5], v[20:21], 0, v[8:9]
	v_mov_b32_e32 v15, v9
	v_and_b32_sdwa v8, v7, s24 dst_sel:DWORD dst_unused:UNUSED_PAD src0_sel:WORD_1 src1_sel:DWORD
	v_and_b32_sdwa v17, v7, s23 dst_sel:DWORD dst_unused:UNUSED_PAD src0_sel:WORD_1 src1_sel:DWORD
	v_lshlrev_b32_e32 v16, 5, v18
	v_lshl_add_u64 v[4:5], v[4:5], 0, v[14:15]
	v_or_b32_e32 v7, v1, v8
	v_or_b32_e32 v8, v6, v8
	s_mov_b32 s12, 1
	s_mov_b32 s13, 0
	s_mov_b32 s20, 32
	v_readlane_b32 s37, v252, 49
	v_readlane_b32 s38, v252, 50
	v_readlane_b32 s39, v252, 51
	v_readlane_b32 s40, v252, 52
	v_readlane_b32 s41, v252, 53
	v_readlane_b32 s42, v252, 54
	v_readlane_b32 s43, v252, 55
	v_readlane_b32 s44, v252, 56
	v_readlane_b32 s45, v252, 57
	v_readlane_b32 s48, v252, 60
	v_readlane_b32 s49, v252, 61
	v_readlane_b32 s50, v252, 62
	v_readlane_b32 s51, v252, 63
.Lt_48:
	s_lshl_b32 s21, s12, 1
	s_lshl_b32 s33, s13, 1
	v_or_b32_e32 v15, s21, v7
	v_or_b32_e32 v19, s33, v8
	s_add_i32 s34, s21, 4
	s_add_i32 s35, s33, 4
	s_add_i32 s36, s21, 8
	s_add_i32 s37, s33, 8
	s_add_i32 s38, s21, 12
	s_add_i32 s39, s33, 12
	s_add_i32 s40, s21, 16
	s_add_i32 s41, s33, 16
	s_add_i32 s42, s21, 20
	s_add_i32 s43, s33, 20
	s_add_i32 s44, s21, 24
	s_add_i32 s45, s33, 24
	s_add_i32 s46, s21, 28
	s_add_i32 s47, s33, 28
	v_mad_u64_u32 v[20:21], s[30:31], v19, s25, v[4:5]
	v_mad_u64_u32 v[22:23], s[30:31], v15, s25, v[4:5]
	v_or_b32_e32 v15, s34, v7
	v_or_b32_e32 v19, s35, v8
	v_or_b32_e32 v40, s36, v7
	v_or_b32_e32 v38, s37, v8
	v_or_b32_e32 v44, s38, v7
	v_or_b32_e32 v42, s39, v8
	v_or_b32_e32 v48, s40, v7
	v_or_b32_e32 v46, s41, v8
	v_or_b32_e32 v52, s42, v7
	v_or_b32_e32 v50, s43, v8
	v_or_b32_e32 v56, s44, v7
	v_or_b32_e32 v54, s45, v8
	v_or_b32_e32 v60, s46, v7
	v_or_b32_e32 v58, s47, v8
	v_mad_u64_u32 v[34:35], s[30:31], v19, s25, v[4:5]
	v_mad_u64_u32 v[36:37], s[30:31], v15, s25, v[4:5]
	v_mad_u64_u32 v[38:39], s[30:31], v38, s25, v[4:5]
	v_mad_u64_u32 v[40:41], s[30:31], v40, s25, v[4:5]
	v_mad_u64_u32 v[42:43], s[30:31], v42, s25, v[4:5]
	v_mad_u64_u32 v[44:45], s[30:31], v44, s25, v[4:5]
	v_mad_u64_u32 v[46:47], s[30:31], v46, s25, v[4:5]
	v_mad_u64_u32 v[48:49], s[30:31], v48, s25, v[4:5]
	v_mad_u64_u32 v[50:51], s[30:31], v50, s25, v[4:5]
	v_mad_u64_u32 v[52:53], s[30:31], v52, s25, v[4:5]
	v_mad_u64_u32 v[54:55], s[30:31], v54, s25, v[4:5]
	v_mad_u64_u32 v[56:57], s[30:31], v56, s25, v[4:5]
	v_mad_u64_u32 v[58:59], s[30:31], v58, s25, v[4:5]
	v_mad_u64_u32 v[60:61], s[30:31], v60, s25, v[4:5]
	global_load_dword v15, v[20:21], off
	global_load_dword v19, v[22:23], off
	global_load_dword v62, v[34:35], off
	global_load_dword v63, v[36:37], off
	global_load_dword v64, v[38:39], off
	global_load_dword v65, v[40:41], off
	global_load_dword v69, v[42:43], off
	global_load_dword v70, v[44:45], off
	global_load_dword v71, v[46:47], off
	global_load_dword v72, v[48:49], off
	global_load_dword v73, v[50:51], off
	global_load_dword v74, v[52:53], off
	global_load_dword v75, v[54:55], off
	global_load_dword v76, v[56:57], off
	global_load_dword v77, v[58:59], off
	global_load_dword v78, v[60:61], off
	v_or_b32_e32 v22, s21, v1
	v_or_b32_e32 v20, s33, v6
	s_add_i32 s13, s13, 16
	s_add_i32 s12, s12, 16
	s_add_i32 s20, s20, -16
	v_mad_u64_u32 v[20:21], s[30:31], v20, s3, v[10:11]
	v_mad_u64_u32 v[22:23], s[30:31], v22, s3, v[10:11]
	v_or_b32_e32 v21, s34, v1
	v_or_b32_e32 v23, s35, v6
	v_or_b32_e32 v40, s36, v1
	v_or_b32_e32 v38, s37, v6
	v_or_b32_e32 v44, s38, v1
	v_or_b32_e32 v42, s39, v6
	v_or_b32_e32 v48, s40, v1
	v_or_b32_e32 v46, s41, v6
	v_or_b32_e32 v52, s42, v1
	v_or_b32_e32 v50, s43, v6
	v_or_b32_e32 v56, s44, v1
	v_or_b32_e32 v54, s45, v6
	v_or_b32_e32 v60, s46, v1
	v_or_b32_e32 v58, s47, v6
	s_cmp_lg_u32 s20, 0
	v_mad_u64_u32 v[34:35], s[30:31], v23, s3, v[10:11]
	v_mad_u64_u32 v[36:37], s[30:31], v21, s3, v[10:11]
	v_mad_u64_u32 v[38:39], s[30:31], v38, s3, v[10:11]
	v_mad_u64_u32 v[40:41], s[30:31], v40, s3, v[10:11]
	v_mad_u64_u32 v[42:43], s[30:31], v42, s3, v[10:11]
	v_mad_u64_u32 v[44:45], s[30:31], v44, s3, v[10:11]
	v_mad_u64_u32 v[46:47], s[30:31], v46, s3, v[10:11]
	v_mad_u64_u32 v[48:49], s[30:31], v48, s3, v[10:11]
	v_mad_u64_u32 v[50:51], s[30:31], v50, s3, v[10:11]
	v_mad_u64_u32 v[52:53], s[30:31], v52, s3, v[10:11]
	v_mad_u64_u32 v[54:55], s[30:31], v54, s3, v[10:11]
	v_mad_u64_u32 v[56:57], s[30:31], v56, s3, v[10:11]
	v_mad_u64_u32 v[58:59], s[30:31], v58, s3, v[10:11]
	v_mad_u64_u32 v[60:61], s[30:31], v60, s3, v[10:11]
	s_waitcnt vmcnt(15)
	ds_write_b32 v20, v15
	s_waitcnt vmcnt(14)
	ds_write_b32 v22, v19
	s_waitcnt vmcnt(13)
	ds_write_b32 v34, v62
	s_waitcnt vmcnt(12)
	ds_write_b32 v36, v63
	s_waitcnt vmcnt(11)
	ds_write_b32 v38, v64
	s_waitcnt vmcnt(10)
	ds_write_b32 v40, v65
	s_waitcnt vmcnt(9)
	ds_write_b32 v42, v69
	s_waitcnt vmcnt(8)
	ds_write_b32 v44, v70
	s_waitcnt vmcnt(7)
	ds_write_b32 v46, v71
	s_waitcnt vmcnt(6)
	ds_write_b32 v48, v72
	s_waitcnt vmcnt(5)
	ds_write_b32 v50, v73
	s_waitcnt vmcnt(4)
	ds_write_b32 v52, v74
	s_waitcnt vmcnt(3)
	ds_write_b32 v54, v75
	s_waitcnt vmcnt(2)
	ds_write_b32 v56, v76
	s_waitcnt vmcnt(1)
	ds_write_b32 v58, v77
	s_waitcnt vmcnt(0)
	ds_write_b32 v60, v78
	s_cbranch_scc1 .Lt_48

; #define LAS __attribute__((address_space(3)))
; __device__ __forceinline__ unsigned cvt_pk_bf16(float lo, float hi) { unsigned r; asm("v_cvt_pk_bf16_f32 %0, %1, %2" : "=v"(r) : "v"(lo), "v"(hi)); return r; }
; __device__ __forceinline__ int drow_map(int mode, int n) {
;     ...
;     const int r = 256 * (n >> 7) + 128 * ((n >> 2) & 1) + 32 * ((n >> 5) & 3) + 4 * ((n >> 3) & 3) + (n & 3);
;     return mode == 2 ? r : r + 16;
; __device__ __forceinline__ void transpose_item(const float* W, int ldw, int K, bf16_t* WT, int mode, LAS float* scr, int kb, int nb, int lane) {
;     ...
;     asm volatile("s_waitcnt lgkmcnt(0)" ::: "memory");
;     const int c = lane & 7;
; #pragma unroll
;     for (int j = 0; j < 4; ++j) { const int n = (lane >> 3) + 8 * j; const LAS float* s = scr + (8 * c) * 33 + n;
;         u32x4 o; o.x = cvt_pk_bf16(s[0 * 33], s[1 * 33]); o.y = cvt_pk_bf16(s[2 * 33], s[3 * 33]); o.z = cvt_pk_bf16(s[4 * 33], s[5 * 33]); o.w = cvt_pk_bf16(s[6 * 33], s[7 * 33]);
;         *(u32x4*)(WT + (size_t)drow_map(mode, n0 + n) * K + k0 + 8 * c) = o; }
	v_lshl_add_u64 v[2:3], s[6:7], 0, v[2:3]
	s_waitcnt lgkmcnt(0)
	v_lshlrev_b32_sdwa v8, v30, v17 dst_sel:DWORD dst_unused:UNUSED_PAD src0_sel:DWORD src1_sel:WORD_0
	v_lshlrev_b32_e32 v4, 6, v18
	v_lshl_add_u64 v[2:3], v[2:3], 0, v[8:9]
	v_lshlrev_b32_e32 v8, 1, v12
	ds_read2_b32 v[18:19], v24 offset0:33 offset1:41
	ds_read2_b32 v[20:21], v24 offset1:8
	ds_read2_b32 v[22:23], v24 offset0:66 offset1:74
	ds_read2_b32 v[34:35], v24 offset0:99 offset1:107
	ds_read2_b32 v[36:37], v24 offset0:132 offset1:140
	ds_read2_b32 v[38:39], v24 offset0:165 offset1:173
	ds_read2_b32 v[40:41], v24 offset0:198 offset1:206
	ds_read2_b32 v[42:43], v24 offset0:231 offset1:239
	v_and_b32_e32 v7, 0x1f00, v4
	v_lshl_add_u64 v[44:45], v[2:3], 0, v[8:9]
	v_bitop3_b32 v8, v16, s26, v13 bitop3:0xc8
	v_or3_b32 v7, v7, v8, v28
	v_lshlrev_b32_e32 v8, 11, v7
	v_lshl_add_u64 v[16:17], v[44:45], 0, v[8:9]
	s_waitcnt lgkmcnt(6)
	v_cvt_pk_bf16_f32 v2, v20, v18
	s_waitcnt lgkmcnt(4)
	v_cvt_pk_bf16_f32 v3, v22, v34
	s_waitcnt lgkmcnt(2)
	v_cvt_pk_bf16_f32 v4, v36, v38
	s_waitcnt lgkmcnt(0)
	v_cvt_pk_bf16_f32 v5, v40, v42
	global_store_dwordx4 v[16:17], v[2:5], off
	s_movk_i32 s12, 0x2000
	v_add_co_u32_e32 v18, vcc, s12, v16
	v_cvt_pk_bf16_f32 v2, v21, v19
	v_cvt_pk_bf16_f32 v3, v23, v35
	v_cvt_pk_bf16_f32 v4, v37, v39
	v_cvt_pk_bf16_f32 v5, v41, v43
	ds_read2_b32 v[20:21], v24 offset0:16 offset1:24
	ds_read2_b32 v[22:23], v24 offset0:49 offset1:57
	ds_read2_b32 v[34:35], v24 offset0:82 offset1:90
	ds_read2_b32 v[36:37], v24 offset0:115 offset1:123
	ds_read2_b32 v[38:39], v24 offset0:148 offset1:156
	ds_read2_b32 v[40:41], v24 offset0:181 offset1:189
	ds_read2_b32 v[42:43], v24 offset0:214 offset1:222
	ds_read2_b32 v[44:45], v24 offset0:247 offset1:255
	v_addc_co_u32_e32 v19, vcc, 0, v17, vcc
	s_movk_i32 s12, 0x4000
	global_store_dwordx4 v[18:19], v[2:5], off
	v_add_co_u32_e32 v18, vcc, s12, v16
	s_waitcnt lgkmcnt(6)
	v_cvt_pk_bf16_f32 v2, v20, v22
	s_waitcnt lgkmcnt(4)
	v_cvt_pk_bf16_f32 v3, v34, v36
	s_waitcnt lgkmcnt(2)
	v_cvt_pk_bf16_f32 v4, v38, v40
	s_waitcnt lgkmcnt(0)
	v_cvt_pk_bf16_f32 v5, v42, v44
	v_addc_co_u32_e32 v19, vcc, 0, v17, vcc
	v_add_co_u32_e32 v16, vcc, 0x6000, v16
	global_store_dwordx4 v[18:19], v[2:5], off
	s_nop 0
	v_addc_co_u32_e32 v17, vcc, 0, v17, vcc
	v_cvt_pk_bf16_f32 v2, v21, v23
	v_cvt_pk_bf16_f32 v3, v35, v37
	v_cvt_pk_bf16_f32 v4, v39, v41
	v_cvt_pk_bf16_f32 v5, v43, v45
	global_store_dwordx4 v[16:17], v[2:5], off
	s_waitcnt lgkmcnt(0)

; __device__ __forceinline__ void prep_phase(const Params& p, LAS unsigned char* lds) {
;     ...
;             r -= I_IN;
;             if (r < I_OUT) { transpose_item(p.w_out + (size_t)l * DM * DM, DM, DM, (bf16_t*)(ws + WS_WOUT) + (size_t)l * DM * DM, 0, scr, r / 32, r % 32, lane); continue; }
.Lt_51:
	s_andn2_saveexec_b64 s[16:17], s[16:17]
	s_cbranch_execz .Lt_55

; #define LAS __attribute__((address_space(3)))
; __device__ __forceinline__ void transpose_item(const float* W, int ldw, int K, bf16_t* WT, int mode, LAS float* scr, int kb, int nb, int lane) {
;     const int k0 = 64 * kb, n0 = 32 * nb;
; #pragma unroll 8
;     for (int i = 0; i < 32; ++i) { const int kk = 2 * i + (lane >> 5); scr[kk * 33 + (lane & 31)] = W[(size_t)(k0 + kk) * ldw + n0 + (lane & 31)]; }
; __device__ __forceinline__ void prep_phase(const Params& p, LAS unsigned char* lds) {
;     ...
;             if (r < I_OUT) { transpose_item(p.w_out + (size_t)l * DM * DM, DM, DM, (bf16_t*)(ws + WS_WOUT) + (size_t)l * DM * DM, 0, scr, r / 32, r % 32, lane); continue; }
	v_readlane_b32 s36, v252, 48
	v_lshlrev_b32_e32 v4, 1, v5
	v_lshlrev_b32_e32 v5, 5, v5
	v_lshlrev_b64 v[2:3], 20, v[16:17]
	v_lshlrev_b64 v[16:17], 22, v[16:17]
	v_readlane_b32 s44, v252, 56
	v_readlane_b32 s45, v252, 57
	v_and_b32_e32 v7, 0x3e0, v5
	v_and_b32_e32 v4, 0xfc0, v4
	v_lshl_add_u64 v[16:17], s[44:45], 0, v[16:17]
	v_lshlrev_b32_e32 v8, 2, v7
	v_add_u32_e32 v4, 0xfffff700, v4
	v_lshl_add_u64 v[16:17], v[16:17], 0, v[8:9]
	v_mov_b32_e32 v15, v9
	s_mov_b32 s18, 1
	v_lshl_add_u64 v[16:17], v[16:17], 0, v[14:15]
	v_or_b32_e32 v5, v1, v4
	v_or_b32_e32 v8, v6, v4
	s_mov_b32 s19, 0
	s_mov_b32 s20, 32
	v_readlane_b32 s37, v252, 49
	v_readlane_b32 s38, v252, 50
	v_readlane_b32 s39, v252, 51
	v_readlane_b32 s40, v252, 52
	v_readlane_b32 s41, v252, 53
	v_readlane_b32 s42, v252, 54
	v_readlane_b32 s43, v252, 55
	v_readlane_b32 s46, v252, 58
	v_readlane_b32 s47, v252, 59
	v_readlane_b32 s48, v252, 60
	v_readlane_b32 s49, v252, 61
	v_readlane_b32 s50, v252, 62
	v_readlane_b32 s51, v252, 63
.Lt_53:
	s_lshl_b32 s21, s18, 1
	s_lshl_b32 s30, s19, 1
	v_or_b32_e32 v20, s30, v8
	s_add_i32 s31, s21, 4
	s_add_i32 s33, s30, 4
	s_add_i32 s12, s21, 8
	s_add_i32 s13, s30, 8
	s_add_i32 s36, s21, 12
	s_add_i32 s37, s30, 12
	s_add_i32 s38, s21, 16
	s_add_i32 s39, s30, 16
	s_add_i32 s40, s21, 20
	s_add_i32 s41, s30, 20
	s_add_i32 s42, s21, 24
	s_add_i32 s43, s30, 24
	s_add_i32 s44, s21, 28
	s_add_i32 s45, s30, 28
	v_or_b32_e32 v18, s21, v5
	v_ashrrev_i32_e32 v21, 31, v20
	v_or_b32_e32 v22, s31, v5
	v_or_b32_e32 v34, s33, v8
	v_or_b32_e32 v36, s12, v5
	v_or_b32_e32 v38, s13, v8
	v_or_b32_e32 v40, s36, v5
	v_or_b32_e32 v42, s37, v8
	v_or_b32_e32 v44, s38, v5
	v_or_b32_e32 v46, s39, v8
	v_or_b32_e32 v48, s40, v5
	v_or_b32_e32 v50, s41, v8
	v_or_b32_e32 v52, s42, v5
	v_or_b32_e32 v54, s43, v8
	v_or_b32_e32 v56, s44, v5
	v_or_b32_e32 v58, s45, v8
	v_ashrrev_i32_e32 v19, 31, v18
	v_lshlrev_b64 v[20:21], 12, v[20:21]
	v_ashrrev_i32_e32 v35, 31, v34
	v_ashrrev_i32_e32 v23, 31, v22
	v_ashrrev_i32_e32 v39, 31, v38
	v_ashrrev_i32_e32 v37, 31, v36
	v_ashrrev_i32_e32 v43, 31, v42
	v_ashrrev_i32_e32 v41, 31, v40
	v_ashrrev_i32_e32 v47, 31, v46
	v_ashrrev_i32_e32 v45, 31, v44
	v_ashrrev_i32_e32 v51, 31, v50
	v_ashrrev_i32_e32 v49, 31, v48
	v_ashrrev_i32_e32 v55, 31, v54
	v_ashrrev_i32_e32 v53, 31, v52
	v_ashrrev_i32_e32 v59, 31, v58
	v_ashrrev_i32_e32 v57, 31, v56
	v_lshlrev_b64 v[18:19], 12, v[18:19]
	v_lshl_add_u64 v[20:21], v[16:17], 0, v[20:21]
	v_lshlrev_b64 v[22:23], 12, v[22:23]
	v_lshlrev_b64 v[34:35], 12, v[34:35]
	v_lshlrev_b64 v[36:37], 12, v[36:37]
	v_lshlrev_b64 v[38:39], 12, v[38:39]
	v_lshlrev_b64 v[40:41], 12, v[40:41]
	v_lshlrev_b64 v[42:43], 12, v[42:43]
	v_lshlrev_b64 v[44:45], 12, v[44:45]
	v_lshlrev_b64 v[46:47], 12, v[46:47]
	v_lshlrev_b64 v[48:49], 12, v[48:49]
	v_lshlrev_b64 v[50:51], 12, v[50:51]
	v_lshlrev_b64 v[52:53], 12, v[52:53]
	v_lshlrev_b64 v[54:55], 12, v[54:55]
	v_lshlrev_b64 v[56:57], 12, v[56:57]
	v_lshlrev_b64 v[58:59], 12, v[58:59]
	v_lshl_add_u64 v[18:19], v[16:17], 0, v[18:19]
	v_lshl_add_u64 v[34:35], v[16:17], 0, v[34:35]
	v_lshl_add_u64 v[22:23], v[16:17], 0, v[22:23]
	v_lshl_add_u64 v[38:39], v[16:17], 0, v[38:39]
	v_lshl_add_u64 v[36:37], v[16:17], 0, v[36:37]
	v_lshl_add_u64 v[42:43], v[16:17], 0, v[42:43]
	v_lshl_add_u64 v[40:41], v[16:17], 0, v[40:41]
	v_lshl_add_u64 v[46:47], v[16:17], 0, v[46:47]
	v_lshl_add_u64 v[44:45], v[16:17], 0, v[44:45]
	v_lshl_add_u64 v[50:51], v[16:17], 0, v[50:51]
	v_lshl_add_u64 v[48:49], v[16:17], 0, v[48:49]
	v_lshl_add_u64 v[54:55], v[16:17], 0, v[54:55]
	v_lshl_add_u64 v[52:53], v[16:17], 0, v[52:53]
	v_lshl_add_u64 v[58:59], v[16:17], 0, v[58:59]
	v_lshl_add_u64 v[56:57], v[16:17], 0, v[56:57]
	global_load_dword v15, v[20:21], off
	global_load_dword v60, v[18:19], off
	global_load_dword v61, v[34:35], off
	global_load_dword v62, v[22:23], off
	global_load_dword v63, v[38:39], off
	global_load_dword v64, v[36:37], off
	global_load_dword v65, v[42:43], off
	global_load_dword v69, v[40:41], off
	global_load_dword v70, v[46:47], off
	global_load_dword v71, v[44:45], off
	global_load_dword v72, v[50:51], off
	global_load_dword v73, v[48:49], off
	global_load_dword v74, v[54:55], off
	global_load_dword v75, v[52:53], off
	global_load_dword v76, v[58:59], off
	global_load_dword v77, v[56:57], off
	v_or_b32_e32 v20, s21, v1
	v_or_b32_e32 v18, s30, v6
	s_add_i32 s19, s19, 16
	s_add_i32 s18, s18, 16
	s_add_i32 s20, s20, -16
	v_mad_u64_u32 v[18:19], s[34:35], v18, s3, v[10:11]
	v_mad_u64_u32 v[20:21], s[34:35], v20, s3, v[10:11]
	v_or_b32_e32 v19, s31, v1
	v_or_b32_e32 v21, s33, v6
	v_or_b32_e32 v38, s12, v1
	v_or_b32_e32 v36, s13, v6
	v_or_b32_e32 v42, s36, v1
	v_or_b32_e32 v40, s37, v6
	v_or_b32_e32 v46, s38, v1
	v_or_b32_e32 v44, s39, v6
	v_or_b32_e32 v50, s40, v1
	v_or_b32_e32 v48, s41, v6
	v_or_b32_e32 v54, s42, v1
	v_or_b32_e32 v52, s43, v6
	v_or_b32_e32 v58, s44, v1
	v_or_b32_e32 v56, s45, v6
	s_cmp_lg_u32 s20, 0
	v_mad_u64_u32 v[22:23], s[12:13], v21, s3, v[10:11]
	v_mad_u64_u32 v[34:35], s[12:13], v19, s3, v[10:11]
	v_mad_u64_u32 v[36:37], s[12:13], v36, s3, v[10:11]
	v_mad_u64_u32 v[38:39], s[12:13], v38, s3, v[10:11]
	v_mad_u64_u32 v[40:41], s[12:13], v40, s3, v[10:11]
	v_mad_u64_u32 v[42:43], s[12:13], v42, s3, v[10:11]
	v_mad_u64_u32 v[44:45], s[12:13], v44, s3, v[10:11]
	v_mad_u64_u32 v[46:47], s[12:13], v46, s3, v[10:11]
	v_mad_u64_u32 v[48:49], s[12:13], v48, s3, v[10:11]
	v_mad_u64_u32 v[50:51], s[12:13], v50, s3, v[10:11]
	v_mad_u64_u32 v[52:53], s[12:13], v52, s3, v[10:11]
	v_mad_u64_u32 v[54:55], s[12:13], v54, s3, v[10:11]
	v_mad_u64_u32 v[56:57], s[12:13], v56, s3, v[10:11]
	v_mad_u64_u32 v[58:59], s[12:13], v58, s3, v[10:11]
	s_waitcnt vmcnt(15)
	ds_write_b32 v18, v15
	s_waitcnt vmcnt(14)
	ds_write_b32 v20, v60
	s_waitcnt vmcnt(13)
	ds_write_b32 v22, v61
	s_waitcnt vmcnt(12)
	ds_write_b32 v34, v62
	s_waitcnt vmcnt(11)
	ds_write_b32 v36, v63
	s_waitcnt vmcnt(10)
	ds_write_b32 v38, v64
	s_waitcnt vmcnt(9)
	ds_write_b32 v40, v65
	s_waitcnt vmcnt(8)
	ds_write_b32 v42, v69
	s_waitcnt vmcnt(7)
	ds_write_b32 v44, v70
	s_waitcnt vmcnt(6)
	ds_write_b32 v46, v71
	s_waitcnt vmcnt(5)
	ds_write_b32 v48, v72
	s_waitcnt vmcnt(4)
	ds_write_b32 v50, v73
	s_waitcnt vmcnt(3)
	ds_write_b32 v52, v74
	s_waitcnt vmcnt(2)
	ds_write_b32 v54, v75
	s_waitcnt vmcnt(1)
	ds_write_b32 v56, v76
	s_waitcnt vmcnt(0)
	ds_write_b32 v58, v77
	s_cbranch_scc1 .Lt_53

; #define LAS __attribute__((address_space(3)))
; __device__ __forceinline__ unsigned cvt_pk_bf16(float lo, float hi) { unsigned r; asm("v_cvt_pk_bf16_f32 %0, %1, %2" : "=v"(r) : "v"(lo), "v"(hi)); return r; }
; __device__ __forceinline__ void transpose_item(const float* W, int ldw, int K, bf16_t* WT, int mode, LAS float* scr, int kb, int nb, int lane) {
;     ...
;     asm volatile("s_waitcnt lgkmcnt(0)" ::: "memory");
;     const int c = lane & 7;
; #pragma unroll
;     for (int j = 0; j < 4; ++j) { const int n = (lane >> 3) + 8 * j; const LAS float* s = scr + (8 * c) * 33 + n;
;         u32x4 o; o.x = cvt_pk_bf16(s[0 * 33], s[1 * 33]); o.y = cvt_pk_bf16(s[2 * 33], s[3 * 33]); o.z = cvt_pk_bf16(s[4 * 33], s[5 * 33]); o.w = cvt_pk_bf16(s[6 * 33], s[7 * 33]);
;         *(u32x4*)(WT + (size_t)drow_map(mode, n0 + n) * K + k0 + 8 * c) = o; }
	s_waitcnt lgkmcnt(0)
	v_lshl_add_u64 v[2:3], v[2:3], 1, s[8:9]
	v_mov_b32_e32 v5, v9
	ds_read2_b32 v[16:17], v24 offset0:33 offset1:41
	ds_read2_b32 v[18:19], v24 offset1:8
	ds_read2_b32 v[20:21], v24 offset0:66 offset1:74
	ds_read2_b32 v[22:23], v24 offset0:99 offset1:107
	ds_read2_b32 v[34:35], v24 offset0:132 offset1:140
	ds_read2_b32 v[36:37], v24 offset0:165 offset1:173
	ds_read2_b32 v[38:39], v24 offset0:198 offset1:206
	ds_read2_b32 v[40:41], v24 offset0:231 offset1:239
	v_lshl_add_u64 v[2:3], v[4:5], 1, v[2:3]
	v_lshlrev_b32_e32 v8, 1, v12
	v_lshl_add_u64 v[42:43], v[2:3], 0, v[8:9]
	v_or_b32_e32 v8, v7, v13
	v_lshlrev_b32_e32 v8, 11, v8
	v_lshl_add_u64 v[44:45], v[42:43], 0, v[8:9]
	s_waitcnt lgkmcnt(6)
	v_cvt_pk_bf16_f32 v2, v18, v16
	s_waitcnt lgkmcnt(4)
	v_cvt_pk_bf16_f32 v3, v20, v22
	s_waitcnt lgkmcnt(2)
	v_cvt_pk_bf16_f32 v4, v34, v36
	s_waitcnt lgkmcnt(0)
	v_cvt_pk_bf16_f32 v5, v38, v40
	global_store_dwordx4 v[44:45], v[2:5], off
	v_or_b32_e32 v8, v7, v25
	v_lshlrev_b32_e32 v8, 11, v8
	v_cvt_pk_bf16_f32 v2, v19, v17
	v_cvt_pk_bf16_f32 v3, v21, v23
	v_cvt_pk_bf16_f32 v4, v35, v37
	v_cvt_pk_bf16_f32 v5, v39, v41
	ds_read2_b32 v[18:19], v24 offset0:16 offset1:24
	ds_read2_b32 v[20:21], v24 offset0:49 offset1:57
	ds_read2_b32 v[22:23], v24 offset0:82 offset1:90
	ds_read2_b32 v[34:35], v24 offset0:115 offset1:123
	ds_read2_b32 v[36:37], v24 offset0:148 offset1:156
	ds_read2_b32 v[38:39], v24 offset0:181 offset1:189
	ds_read2_b32 v[40:41], v24 offset0:214 offset1:222
	ds_read2_b32 v[44:45], v24 offset0:247 offset1:255
	v_lshl_add_u64 v[16:17], v[42:43], 0, v[8:9]
	v_or_b32_e32 v8, v7, v26
	v_lshlrev_b32_e32 v8, 11, v8
	v_or_b32_e32 v7, v7, v27
	global_store_dwordx4 v[16:17], v[2:5], off
	v_lshl_add_u64 v[16:17], v[42:43], 0, v[8:9]
	v_lshlrev_b32_e32 v8, 11, v7
	s_waitcnt lgkmcnt(6)
	v_cvt_pk_bf16_f32 v2, v18, v20
	s_waitcnt lgkmcnt(4)
	v_cvt_pk_bf16_f32 v3, v22, v34
	s_waitcnt lgkmcnt(2)
	v_cvt_pk_bf16_f32 v4, v36, v38
	s_waitcnt lgkmcnt(0)
	v_cvt_pk_bf16_f32 v5, v40, v44
	global_store_dwordx4 v[16:17], v[2:5], off
	v_lshl_add_u64 v[16:17], v[42:43], 0, v[8:9]
	s_nop 0
	v_cvt_pk_bf16_f32 v2, v19, v21
	v_cvt_pk_bf16_f32 v3, v23, v35
	v_cvt_pk_bf16_f32 v4, v37, v39
	v_cvt_pk_bf16_f32 v5, v41, v45
	global_store_dwordx4 v[16:17], v[2:5], off
	s_waitcnt lgkmcnt(0)

; __device__ __forceinline__ void prep_phase(const Params& p, LAS unsigned char* lds) {
;     ...
;             if (r < I_IN) { const int kb = r / 72, nb = r % 72; if (nb >= 48 && nb < 56) continue;
;                 transpose_item(p.w_in + (size_t)l * DM * INW_SRC, INW_SRC, DM, (bf16_t*)(ws + WS_WIN) + (size_t)l * INW * DM, 1, scr, kb, nb, lane); continue; }
.Lt_56:
	s_andn2_saveexec_b64 s[14:15], s[14:15]
	s_cbranch_execz .Lt_33

; __device__ __forceinline__ void prep_phase(const Params& p, LAS unsigned char* lds) {
;     ...
;             if (r < I_IN) { const int kb = r / 72, nb = r % 72; if (nb >= 48 && nb < 56) continue;
	v_mul_i32_i24_e32 v2, 0xe39, v5
	v_lshrrev_b32_e32 v3, 31, v2
	v_ashrrev_i32_e32 v2, 18, v2
	v_add_u16_e32 v2, v2, v3
	v_mul_lo_u16_e32 v3, 0x48, v2
	v_sub_u16_e32 v3, v5, v3
	v_and_b32_e32 v4, -8, v3
	v_cmp_ne_u16_e32 vcc, 48, v4
	s_and_saveexec_b64 s[16:17], vcc
	s_cbranch_execz .Lt_32

; #define LAS __attribute__((address_space(3)))
; __device__ __forceinline__ void transpose_item(const float* W, int ldw, int K, bf16_t* WT, int mode, LAS float* scr, int kb, int nb, int lane) {
;     const int k0 = 64 * kb, n0 = 32 * nb;
; #pragma unroll 8
;     for (int i = 0; i < 32; ++i) { const int kk = 2 * i + (lane >> 5); scr[kk * 33 + (lane & 31)] = W[(size_t)(k0 + kk) * ldw + n0 + (lane & 31)]; }
; __device__ __forceinline__ void prep_phase(const Params& p, LAS unsigned char* lds) {
;     ...
;                 transpose_item(p.w_in + (size_t)l * DM * INW_SRC, INW_SRC, DM, (bf16_t*)(ws + WS_WIN) + (size_t)l * INW * DM, 1, scr, kb, nb, lane); continue; }
	v_readlane_b32 s36, v252, 32
	v_readlane_b32 s37, v252, 33
	s_mov_b32 s12, 0x900000
	v_lshlrev_b32_sdwa v18, v32, sext(v3) dst_sel:DWORD dst_unused:UNUSED_PAD src0_sel:DWORD src1_sel:WORD_0
	v_mov_b64_e32 v[4:5], s[36:37]
	v_mad_i64_i32 v[4:5], s[12:13], v16, s12, v[4:5]
	v_ashrrev_i32_e32 v19, 31, v18
	v_lshlrev_b32_sdwa v20, v31, sext(v2) dst_sel:DWORD dst_unused:UNUSED_PAD src0_sel:DWORD src1_sel:WORD_0
	v_lshl_add_u64 v[2:3], v[18:19], 2, v[4:5]
	v_mov_b32_e32 v15, v9
	v_lshl_add_u64 v[2:3], v[2:3], 0, v[14:15]
	v_or_b32_e32 v5, v1, v20
	v_or_b32_e32 v4, v6, v20
	s_mov_b32 s12, 1
	s_mov_b32 s13, 0
	s_mov_b32 s18, 32
	v_readlane_b32 s38, v252, 34
	v_readlane_b32 s39, v252, 35
	v_readlane_b32 s40, v252, 36
	v_readlane_b32 s41, v252, 37
	v_readlane_b32 s42, v252, 38
	v_readlane_b32 s43, v252, 39
	v_readlane_b32 s44, v252, 40
	v_readlane_b32 s45, v252, 41
	v_readlane_b32 s46, v252, 42
	v_readlane_b32 s47, v252, 43
	v_readlane_b32 s48, v252, 44
	v_readlane_b32 s49, v252, 45
	v_readlane_b32 s50, v252, 46
	v_readlane_b32 s51, v252, 47
.Lt_59:
	s_lshl_b32 s19, s12, 1
	s_lshl_b32 s30, s13, 1
	v_or_b32_e32 v7, s19, v5
	v_or_b32_e32 v8, s30, v4
	s_add_i32 s31, s19, 4
	s_add_i32 s33, s30, 4
	s_add_i32 s34, s19, 8
	s_add_i32 s35, s30, 8
	s_add_i32 s36, s19, 12
	s_add_i32 s37, s30, 12
	s_add_i32 s38, s19, 16
	s_add_i32 s39, s30, 16
	s_add_i32 s40, s19, 20
	s_add_i32 s41, s30, 20
	s_add_i32 s42, s19, 24
	s_add_i32 s43, s30, 24
	s_add_i32 s44, s19, 28
	s_add_i32 s45, s30, 28
	v_mad_i64_i32 v[22:23], s[20:21], v8, s27, v[2:3]
	v_mad_i64_i32 v[34:35], s[20:21], v7, s27, v[2:3]
	v_or_b32_e32 v7, s31, v5
	v_or_b32_e32 v8, s33, v4
	v_or_b32_e32 v15, s34, v5
	v_or_b32_e32 v17, s35, v4
	v_or_b32_e32 v19, s36, v5
	v_or_b32_e32 v21, s37, v4
	v_or_b32_e32 v50, s38, v5
	v_or_b32_e32 v48, s39, v4
	v_or_b32_e32 v54, s40, v5
	v_or_b32_e32 v52, s41, v4
	v_or_b32_e32 v58, s42, v5
	v_or_b32_e32 v56, s43, v4
	v_or_b32_e32 v62, s44, v5
	v_or_b32_e32 v60, s45, v4
	v_mad_i64_i32 v[36:37], s[20:21], v8, s27, v[2:3]
	v_mad_i64_i32 v[38:39], s[20:21], v7, s27, v[2:3]
	v_mad_i64_i32 v[40:41], s[20:21], v17, s27, v[2:3]
	v_mad_i64_i32 v[42:43], s[20:21], v15, s27, v[2:3]
	v_mad_i64_i32 v[44:45], s[20:21], v21, s27, v[2:3]
	v_mad_i64_i32 v[46:47], s[20:21], v19, s27, v[2:3]
	v_mad_i64_i32 v[48:49], s[20:21], v48, s27, v[2:3]
	v_mad_i64_i32 v[50:51], s[20:21], v50, s27, v[2:3]
	v_mad_i64_i32 v[52:53], s[20:21], v52, s27, v[2:3]
	v_mad_i64_i32 v[54:55], s[20:21], v54, s27, v[2:3]
	v_mad_i64_i32 v[56:57], s[20:21], v56, s27, v[2:3]
	v_mad_i64_i32 v[58:59], s[20:21], v58, s27, v[2:3]
	v_mad_i64_i32 v[60:61], s[20:21], v60, s27, v[2:3]
	v_mad_i64_i32 v[62:63], s[20:21], v62, s27, v[2:3]
	global_load_dword v7, v[22:23], off
	global_load_dword v8, v[34:35], off
	global_load_dword v15, v[36:37], off
	global_load_dword v17, v[38:39], off
	global_load_dword v19, v[40:41], off
	global_load_dword v21, v[42:43], off
	global_load_dword v64, v[44:45], off
	global_load_dword v65, v[46:47], off
	global_load_dword v69, v[48:49], off
	global_load_dword v70, v[50:51], off
	global_load_dword v71, v[52:53], off
	global_load_dword v72, v[54:55], off
	global_load_dword v73, v[56:57], off
	global_load_dword v74, v[58:59], off
	global_load_dword v75, v[60:61], off
	global_load_dword v76, v[62:63], off
	v_or_b32_e32 v34, s19, v1
	v_or_b32_e32 v22, s30, v6
	s_add_i32 s13, s13, 16
	s_add_i32 s12, s12, 16
	s_add_i32 s18, s18, -16
	v_mad_u64_u32 v[22:23], s[20:21], v22, s3, v[10:11]
	v_mad_u64_u32 v[34:35], s[20:21], v34, s3, v[10:11]
	v_or_b32_e32 v23, s31, v1
	v_or_b32_e32 v35, s33, v6
	v_or_b32_e32 v42, s34, v1
	v_or_b32_e32 v40, s35, v6
	v_or_b32_e32 v46, s36, v1
	v_or_b32_e32 v44, s37, v6
	v_or_b32_e32 v50, s38, v1
	v_or_b32_e32 v48, s39, v6
	v_or_b32_e32 v54, s40, v1
	v_or_b32_e32 v52, s41, v6
	v_or_b32_e32 v58, s42, v1
	v_or_b32_e32 v56, s43, v6
	v_or_b32_e32 v62, s44, v1
	v_or_b32_e32 v60, s45, v6
	s_cmp_lg_u32 s18, 0
	v_mad_u64_u32 v[36:37], s[20:21], v35, s3, v[10:11]
	v_mad_u64_u32 v[38:39], s[20:21], v23, s3, v[10:11]
	v_mad_u64_u32 v[40:41], s[20:21], v40, s3, v[10:11]
	v_mad_u64_u32 v[42:43], s[20:21], v42, s3, v[10:11]
	v_mad_u64_u32 v[44:45], s[20:21], v44, s3, v[10:11]
	v_mad_u64_u32 v[46:47], s[20:21], v46, s3, v[10:11]
	v_mad_u64_u32 v[48:49], s[20:21], v48, s3, v[10:11]
	v_mad_u64_u32 v[50:51], s[20:21], v50, s3, v[10:11]
	v_mad_u64_u32 v[52:53], s[20:21], v52, s3, v[10:11]
	v_mad_u64_u32 v[54:55], s[20:21], v54, s3, v[10:11]
	v_mad_u64_u32 v[56:57], s[20:21], v56, s3, v[10:11]
	v_mad_u64_u32 v[58:59], s[20:21], v58, s3, v[10:11]
	v_mad_u64_u32 v[60:61], s[20:21], v60, s3, v[10:11]
	v_mad_u64_u32 v[62:63], s[20:21], v62, s3, v[10:11]
	s_waitcnt vmcnt(15)
	ds_write_b32 v22, v7
	s_waitcnt vmcnt(14)
	ds_write_b32 v34, v8
	s_waitcnt vmcnt(13)
	ds_write_b32 v36, v15
	s_waitcnt vmcnt(12)
	ds_write_b32 v38, v17
	s_waitcnt vmcnt(11)
	ds_write_b32 v40, v19
	s_waitcnt vmcnt(10)
	ds_write_b32 v42, v21
	s_waitcnt vmcnt(9)
	ds_write_b32 v44, v64
	s_waitcnt vmcnt(8)
	ds_write_b32 v46, v65
	s_waitcnt vmcnt(7)
	ds_write_b32 v48, v69
	s_waitcnt vmcnt(6)
	ds_write_b32 v50, v70
	s_waitcnt vmcnt(5)
	ds_write_b32 v52, v71
	s_waitcnt vmcnt(4)
	ds_write_b32 v54, v72
	s_waitcnt vmcnt(3)
	ds_write_b32 v56, v73
	s_waitcnt vmcnt(2)
	ds_write_b32 v58, v74
	s_waitcnt vmcnt(1)
	ds_write_b32 v60, v75
	s_waitcnt vmcnt(0)
	ds_write_b32 v62, v76
	s_cbranch_scc1 .Lt_59

; #define LAS __attribute__((address_space(3)))
; __device__ __forceinline__ unsigned cvt_pk_bf16(float lo, float hi) { unsigned r; asm("v_cvt_pk_bf16_f32 %0, %1, %2" : "=v"(r) : "v"(lo), "v"(hi)); return r; }
; __device__ __forceinline__ int drow_map(int mode, int n) {
;     ...
;         if (n < 1024) { const int cs = n & 255, head = cs >> 6, d = cs & 63, a = d >> 5, pp = (d >> 4) & 1, f = d & 15;
;             return (n & ~255) + 128 * ((f >> 2) & 1) + 32 * head + 16 * pp + 4 * (2 * a + (f >> 3)) + (f & 3); }
;         if (n < 1792) return n;
;         { const int mm = n - 1792, cs = mm & 255;
;           return 2048 + (mm & ~255) + 128 * ((cs >> 2) & 1) + 32 * ((cs >> 5) & 3) + 16 * (cs >> 7) + 4 * ((cs >> 3) & 3) + (cs & 3); }
; __device__ __forceinline__ void transpose_item(const float* W, int ldw, int K, bf16_t* WT, int mode, LAS float* scr, int kb, int nb, int lane) {
;     ...
;     asm volatile("s_waitcnt lgkmcnt(0)" ::: "memory");
;     const int c = lane & 7;
; #pragma unroll
;     for (int j = 0; j < 4; ++j) { const int n = (lane >> 3) + 8 * j; const LAS float* s = scr + (8 * c) * 33 + n;
;         u32x4 o; o.x = cvt_pk_bf16(s[0 * 33], s[1 * 33]); o.y = cvt_pk_bf16(s[2 * 33], s[3 * 33]); o.z = cvt_pk_bf16(s[4 * 33], s[5 * 33]); o.w = cvt_pk_bf16(s[6 * 33], s[7 * 33]);
;         *(u32x4*)(WT + (size_t)drow_map(mode, n0 + n) * K + k0 + 8 * c) = o; }
	v_lshrrev_b32_e32 v2, 3, v18
	s_waitcnt lgkmcnt(0)
	v_and_b32_e32 v2, 16, v2
	s_mov_b32 s12, 0x7fffff60
	v_and_or_b32 v7, v18, s12, v2
	ds_read2_b32 v[2:3], v24 offset1:33
	ds_read2_b32 v[4:5], v24 offset0:66 offset1:99
	ds_read2_b32 v[22:23], v24 offset0:132 offset1:165
	ds_read2_b32 v[34:35], v24 offset0:198 offset1:231
	v_or_b32_e32 v8, v18, v13
	v_add_u32_e32 v7, 0x100, v7
	v_cmp_lt_i32_e32 vcc, s28, v8
	s_waitcnt lgkmcnt(3)
	v_cvt_pk_bf16_f32 v2, v2, v3
	s_waitcnt lgkmcnt(2)
	v_cvt_pk_bf16_f32 v3, v4, v5
	s_waitcnt lgkmcnt(1)
	v_cvt_pk_bf16_f32 v4, v22, v23
	s_waitcnt lgkmcnt(0)
	v_cvt_pk_bf16_f32 v5, v34, v35
	s_and_saveexec_b64 s[12:13], vcc
	s_xor_b64 s[18:19], exec, s[12:13]

; __device__ __forceinline__ int drow_map(int mode, int n) {
;     ...
;         if (n < 1024) { const int cs = n & 255, head = cs >> 6, d = cs & 63, a = d >> 5, pp = (d >> 4) & 1, f = d & 15;
;             return (n & ~255) + 128 * ((f >> 2) & 1) + 32 * head + 16 * pp + 4 * (2 * a + (f >> 3)) + (f & 3); }
;         if (n < 1792) return n;
;         { const int mm = n - 1792, cs = mm & 255;
;           return 2048 + (mm & ~255) + 128 * ((cs >> 2) & 1) + 32 * ((cs >> 5) & 3) + 16 * (cs >> 7) + 4 * ((cs >> 3) & 3) + (cs & 3); }
	v_lshlrev_b32_e32 v15, 5, v8
	v_and_b32_e32 v15, 0x80, v15
	v_or3_b32 v15, v15, v29, v7
	v_cmp_gt_u32_e32 vcc, s29, v18
	s_nop 1
	v_cndmask_b32_e32 v22, v15, v8, vcc

; __device__ __forceinline__ int drow_map(int mode, int n) {
;     ...
;         if (n < 1024) { const int cs = n & 255, head = cs >> 6, d = cs & 63, a = d >> 5, pp = (d >> 4) & 1, f = d & 15;
;             return (n & ~255) + 128 * ((f >> 2) & 1) + 32 * head + 16 * pp + 4 * (2 * a + (f >> 3)) + (f & 3); }
	s_or_saveexec_b64 s[18:19], s[18:19]
	v_lshrrev_b32_e32 v15, 4, v18
	v_lshrrev_b32_e32 v17, 1, v18
	v_and_b32_e32 v15, 2, v15
	s_movk_i32 s12, 0x60
	v_and_or_b32 v19, v17, s12, v28
	v_lshlrev_b32_e32 v34, 2, v15
	s_xor_b64 exec, exec, s[18:19]

; __device__ __forceinline__ int drow_map(int mode, int n) {
;     ...
;         if (n < 1024) { const int cs = n & 255, head = cs >> 6, d = cs & 63, a = d >> 5, pp = (d >> 4) & 1, f = d & 15;
;             return (n & ~255) + 128 * ((f >> 2) & 1) + 32 * head + 16 * pp + 4 * (2 * a + (f >> 3)) + (f & 3); }
	v_and_b32_e32 v8, 0xffffff03, v8
	v_or3_b32 v22, v34, v8, v19

; #define LAS __attribute__((address_space(3)))
; __device__ __forceinline__ unsigned cvt_pk_bf16(float lo, float hi) { unsigned r; asm("v_cvt_pk_bf16_f32 %0, %1, %2" : "=v"(r) : "v"(lo), "v"(hi)); return r; }
; __device__ __forceinline__ int drow_map(int mode, int n) {
;     ...
;         if (n < 1024) { const int cs = n & 255, head = cs >> 6, d = cs & 63, a = d >> 5, pp = (d >> 4) & 1, f = d & 15;
;             return (n & ~255) + 128 * ((f >> 2) & 1) + 32 * head + 16 * pp + 4 * (2 * a + (f >> 3)) + (f & 3); }
;         if (n < 1792) return n;
;         { const int mm = n - 1792, cs = mm & 255;
;           return 2048 + (mm & ~255) + 128 * ((cs >> 2) & 1) + 32 * ((cs >> 5) & 3) + 16 * (cs >> 7) + 4 * ((cs >> 3) & 3) + (cs & 3); }
; __device__ __forceinline__ void transpose_item(const float* W, int ldw, int K, bf16_t* WT, int mode, LAS float* scr, int kb, int nb, int lane) {
;     ...
;     asm volatile("s_waitcnt lgkmcnt(0)" ::: "memory");
;     const int c = lane & 7;
; #pragma unroll
;     for (int j = 0; j < 4; ++j) { const int n = (lane >> 3) + 8 * j; const LAS float* s = scr + (8 * c) * 33 + n;
;         u32x4 o; o.x = cvt_pk_bf16(s[0 * 33], s[1 * 33]); o.y = cvt_pk_bf16(s[2 * 33], s[3 * 33]); o.z = cvt_pk_bf16(s[4 * 33], s[5 * 33]); o.w = cvt_pk_bf16(s[6 * 33], s[7 * 33]);
;         *(u32x4*)(WT + (size_t)drow_map(mode, n0 + n) * K + k0 + 8 * c) = o; }
	s_or_b64 exec, exec, s[18:19]
	v_readlane_b32 s36, v252, 0
	v_mul_hi_i32_i24_e32 v17, 0x500000, v16
	v_mul_i32_i24_e32 v16, 0x500000, v16
	v_readlane_b32 s40, v252, 4
	v_readlane_b32 s41, v252, 5
	v_ashrrev_i32_e32 v21, 31, v20
	v_ashrrev_i32_e32 v23, 31, v22
	v_lshl_add_u64 v[16:17], s[40:41], 0, v[16:17]
	v_lshl_add_u64 v[16:17], v[20:21], 1, v[16:17]
	v_lshlrev_b64 v[20:21], 11, v[22:23]
	ds_read2_b32 v[22:23], v24 offset0:8 offset1:41
	ds_read2_b32 v[36:37], v24 offset0:74 offset1:107
	ds_read2_b32 v[38:39], v24 offset0:140 offset1:173
	ds_read2_b32 v[40:41], v24 offset0:206 offset1:239
	v_lshlrev_b32_e32 v8, 1, v12
	v_lshl_add_u64 v[16:17], v[16:17], 0, v[8:9]
	v_or_b32_e32 v8, v18, v25
	v_lshl_add_u64 v[20:21], v[16:17], 0, v[20:21]
	v_cmp_lt_i32_e32 vcc, s28, v8
	v_readlane_b32 s37, v252, 1
	v_readlane_b32 s38, v252, 2
	v_readlane_b32 s39, v252, 3
	v_readlane_b32 s42, v252, 6
	v_readlane_b32 s43, v252, 7
	global_store_dwordx4 v[20:21], v[2:5], off
	s_waitcnt lgkmcnt(3)
	s_nop 0
	v_cvt_pk_bf16_f32 v2, v22, v23
	s_waitcnt lgkmcnt(2)
	v_cvt_pk_bf16_f32 v3, v36, v37
	s_waitcnt lgkmcnt(1)
	v_cvt_pk_bf16_f32 v4, v38, v39
	s_waitcnt lgkmcnt(0)
	v_cvt_pk_bf16_f32 v5, v40, v41
	s_and_saveexec_b64 s[12:13], vcc
	s_xor_b64 s[18:19], exec, s[12:13]

; __device__ __forceinline__ int drow_map(int mode, int n) {
;     ...
;         if (n < 1792) return n;
;         { const int mm = n - 1792, cs = mm & 255;
;           return 2048 + (mm & ~255) + 128 * ((cs >> 2) & 1) + 32 * ((cs >> 5) & 3) + 16 * (cs >> 7) + 4 * ((cs >> 3) & 3) + (cs & 3); }
	v_lshlrev_b32_e32 v20, 5, v8
	v_and_or_b32 v20, v20, s22, v13
	v_or3_b32 v20, v20, v7, 4
	v_cmp_gt_u32_e32 vcc, s29, v18
	s_nop 1
	v_cndmask_b32_e32 v20, v20, v8, vcc

; __device__ __forceinline__ int drow_map(int mode, int n) {
;     ...
;         if (n < 1024) { const int cs = n & 255, head = cs >> 6, d = cs & 63, a = d >> 5, pp = (d >> 4) & 1, f = d & 15;
;             return (n & ~255) + 128 * ((f >> 2) & 1) + 32 * head + 16 * pp + 4 * (2 * a + (f >> 3)) + (f & 3); }
	s_andn2_saveexec_b64 s[18:19], s[18:19]

; __device__ __forceinline__ int drow_map(int mode, int n) {
;     ...
;         if (n < 1024) { const int cs = n & 255, head = cs >> 6, d = cs & 63, a = d >> 5, pp = (d >> 4) & 1, f = d & 15;
;             return (n & ~255) + 128 * ((f >> 2) & 1) + 32 * head + 16 * pp + 4 * (2 * a + (f >> 3)) + (f & 3); }
	v_and_b32_e32 v8, 0xffffff03, v8
	v_lshl_or_b32 v8, v15, 2, v8
	v_or3_b32 v20, v8, v19, 4

; #define LAS __attribute__((address_space(3)))
; __device__ __forceinline__ unsigned cvt_pk_bf16(float lo, float hi) { unsigned r; asm("v_cvt_pk_bf16_f32 %0, %1, %2" : "=v"(r) : "v"(lo), "v"(hi)); return r; }
; __device__ __forceinline__ int drow_map(int mode, int n) {
;     ...
;         if (n < 1024) { const int cs = n & 255, head = cs >> 6, d = cs & 63, a = d >> 5, pp = (d >> 4) & 1, f = d & 15;
;             return (n & ~255) + 128 * ((f >> 2) & 1) + 32 * head + 16 * pp + 4 * (2 * a + (f >> 3)) + (f & 3); }
;         if (n < 1792) return n;
;         { const int mm = n - 1792, cs = mm & 255;
;           return 2048 + (mm & ~255) + 128 * ((cs >> 2) & 1) + 32 * ((cs >> 5) & 3) + 16 * (cs >> 7) + 4 * ((cs >> 3) & 3) + (cs & 3); }
; __device__ __forceinline__ void transpose_item(const float* W, int ldw, int K, bf16_t* WT, int mode, LAS float* scr, int kb, int nb, int lane) {
;     ...
;     asm volatile("s_waitcnt lgkmcnt(0)" ::: "memory");
;     const int c = lane & 7;
; #pragma unroll
;     for (int j = 0; j < 4; ++j) { const int n = (lane >> 3) + 8 * j; const LAS float* s = scr + (8 * c) * 33 + n;
;         u32x4 o; o.x = cvt_pk_bf16(s[0 * 33], s[1 * 33]); o.y = cvt_pk_bf16(s[2 * 33], s[3 * 33]); o.z = cvt_pk_bf16(s[4 * 33], s[5 * 33]); o.w = cvt_pk_bf16(s[6 * 33], s[7 * 33]);
;         *(u32x4*)(WT + (size_t)drow_map(mode, n0 + n) * K + k0 + 8 * c) = o; }
	s_or_b64 exec, exec, s[18:19]
	ds_read2_b32 v[22:23], v24 offset0:16 offset1:49
	ds_read2_b32 v[36:37], v24 offset0:82 offset1:115
	ds_read2_b32 v[38:39], v24 offset0:148 offset1:181
	ds_read2_b32 v[40:41], v24 offset0:214 offset1:247
	v_ashrrev_i32_e32 v21, 31, v20
	v_lshlrev_b64 v[20:21], 11, v[20:21]
	v_or_b32_e32 v8, v18, v26
	v_lshl_add_u64 v[20:21], v[16:17], 0, v[20:21]
	v_cmp_lt_i32_e32 vcc, s28, v8
	global_store_dwordx4 v[20:21], v[2:5], off
	s_waitcnt lgkmcnt(3)
	s_nop 0
	v_cvt_pk_bf16_f32 v2, v22, v23
	s_waitcnt lgkmcnt(2)
	v_cvt_pk_bf16_f32 v3, v36, v37
	s_waitcnt lgkmcnt(1)
	v_cvt_pk_bf16_f32 v4, v38, v39
	s_waitcnt lgkmcnt(0)
	v_cvt_pk_bf16_f32 v5, v40, v41
	s_and_saveexec_b64 s[12:13], vcc
	s_xor_b64 s[18:19], exec, s[12:13]

; __device__ __forceinline__ int drow_map(int mode, int n) {
;     ...
;         if (n < 1792) return n;
;         { const int mm = n - 1792, cs = mm & 255;
;           return 2048 + (mm & ~255) + 128 * ((cs >> 2) & 1) + 32 * ((cs >> 5) & 3) + 16 * (cs >> 7) + 4 * ((cs >> 3) & 3) + (cs & 3); }
	v_lshlrev_b32_e32 v20, 5, v8
	v_and_or_b32 v20, v20, s22, v29
	v_or3_b32 v20, v20, v7, 8
	v_cmp_gt_u32_e32 vcc, s29, v18
	s_nop 1
	v_cndmask_b32_e32 v20, v20, v8, vcc

; __device__ __forceinline__ int drow_map(int mode, int n) {
;     ...
;         if (n < 1024) { const int cs = n & 255, head = cs >> 6, d = cs & 63, a = d >> 5, pp = (d >> 4) & 1, f = d & 15;
;             return (n & ~255) + 128 * ((f >> 2) & 1) + 32 * head + 16 * pp + 4 * (2 * a + (f >> 3)) + (f & 3); }
	s_andn2_saveexec_b64 s[18:19], s[18:19]

; __device__ __forceinline__ int drow_map(int mode, int n) {
;     ...
;         if (n < 1024) { const int cs = n & 255, head = cs >> 6, d = cs & 63, a = d >> 5, pp = (d >> 4) & 1, f = d & 15;
;             return (n & ~255) + 128 * ((f >> 2) & 1) + 32 * head + 16 * pp + 4 * (2 * a + (f >> 3)) + (f & 3); }
	v_and_b32_e32 v8, 0xffffff13, v8
	v_or3_b32 v20, v34, v8, v19

; #define LAS __attribute__((address_space(3)))
; __device__ __forceinline__ unsigned cvt_pk_bf16(float lo, float hi) { unsigned r; asm("v_cvt_pk_bf16_f32 %0, %1, %2" : "=v"(r) : "v"(lo), "v"(hi)); return r; }
; __device__ __forceinline__ int drow_map(int mode, int n) {
;     ...
;         if (n < 1024) { const int cs = n & 255, head = cs >> 6, d = cs & 63, a = d >> 5, pp = (d >> 4) & 1, f = d & 15;
;             return (n & ~255) + 128 * ((f >> 2) & 1) + 32 * head + 16 * pp + 4 * (2 * a + (f >> 3)) + (f & 3); }
;         if (n < 1792) return n;
;         { const int mm = n - 1792, cs = mm & 255;
;           return 2048 + (mm & ~255) + 128 * ((cs >> 2) & 1) + 32 * ((cs >> 5) & 3) + 16 * (cs >> 7) + 4 * ((cs >> 3) & 3) + (cs & 3); }
; __device__ __forceinline__ void transpose_item(const float* W, int ldw, int K, bf16_t* WT, int mode, LAS float* scr, int kb, int nb, int lane) {
;     ...
;     asm volatile("s_waitcnt lgkmcnt(0)" ::: "memory");
;     const int c = lane & 7;
; #pragma unroll
;     for (int j = 0; j < 4; ++j) { const int n = (lane >> 3) + 8 * j; const LAS float* s = scr + (8 * c) * 33 + n;
;         u32x4 o; o.x = cvt_pk_bf16(s[0 * 33], s[1 * 33]); o.y = cvt_pk_bf16(s[2 * 33], s[3 * 33]); o.z = cvt_pk_bf16(s[4 * 33], s[5 * 33]); o.w = cvt_pk_bf16(s[6 * 33], s[7 * 33]);
;         *(u32x4*)(WT + (size_t)drow_map(mode, n0 + n) * K + k0 + 8 * c) = o; }
	s_or_b64 exec, exec, s[18:19]
	ds_read2_b32 v[22:23], v24 offset0:24 offset1:57
	ds_read2_b32 v[34:35], v24 offset0:90 offset1:123
	ds_read2_b32 v[36:37], v24 offset0:156 offset1:189
	ds_read2_b32 v[38:39], v24 offset0:222 offset1:255
	v_ashrrev_i32_e32 v21, 31, v20
	v_lshlrev_b64 v[20:21], 11, v[20:21]
	v_or_b32_e32 v8, v18, v27
	v_lshl_add_u64 v[20:21], v[16:17], 0, v[20:21]
	v_cmp_lt_i32_e32 vcc, s28, v8
	global_store_dwordx4 v[20:21], v[2:5], off
	s_waitcnt lgkmcnt(3)
	s_nop 0
	v_cvt_pk_bf16_f32 v2, v22, v23
	s_waitcnt lgkmcnt(2)
	v_cvt_pk_bf16_f32 v3, v34, v35
	s_waitcnt lgkmcnt(1)
	v_cvt_pk_bf16_f32 v4, v36, v37
	s_waitcnt lgkmcnt(0)
	v_cvt_pk_bf16_f32 v5, v38, v39
	s_and_saveexec_b64 s[12:13], vcc
	s_xor_b64 s[18:19], exec, s[12:13]

; __device__ __forceinline__ int drow_map(int mode, int n) {
;     ...
;         if (n < 1792) return n;
;         { const int mm = n - 1792, cs = mm & 255;
;           return 2048 + (mm & ~255) + 128 * ((cs >> 2) & 1) + 32 * ((cs >> 5) & 3) + 16 * (cs >> 7) + 4 * ((cs >> 3) & 3) + (cs & 3); }
	v_lshlrev_b32_e32 v15, 5, v8
	v_and_or_b32 v15, v15, s22, v13
	v_or3_b32 v7, v15, v7, 12
	v_cmp_gt_u32_e32 vcc, s29, v18
	s_nop 1
	v_cndmask_b32_e32 v20, v7, v8, vcc

; __device__ __forceinline__ int drow_map(int mode, int n) {
;     ...
;         if (n < 1024) { const int cs = n & 255, head = cs >> 6, d = cs & 63, a = d >> 5, pp = (d >> 4) & 1, f = d & 15;
;             return (n & ~255) + 128 * ((f >> 2) & 1) + 32 * head + 16 * pp + 4 * (2 * a + (f >> 3)) + (f & 3); }
	s_andn2_saveexec_b64 s[18:19], s[18:19]
	s_cbranch_execz .Lt_31

; __device__ __forceinline__ int drow_map(int mode, int n) {
;     ...
;         if (n < 1024) { const int cs = n & 255, head = cs >> 6, d = cs & 63, a = d >> 5, pp = (d >> 4) & 1, f = d & 15;
;             return (n & ~255) + 128 * ((f >> 2) & 1) + 32 * head + 16 * pp + 4 * (2 * a + (f >> 3)) + (f & 3); }
; __device__ __forceinline__ void prep_phase(const Params& p, LAS unsigned char* lds) {
;     ...
;         for (int it = gw; it < 2 * I_L; it += NGW) {
	v_and_b32_e32 v7, 0xffffff13, v8
	v_lshl_or_b32 v7, v15, 2, v7
	v_or3_b32 v20, v7, v19, 4
	s_branch .Lt_31
.Lt_76:
	s_mov_b64 exec, -1
	v_readlane_b32 s3, v200, 0
	v_readlane_b32 s4, v200, 1
	v_readlane_b32 s5, v200, 2
	v_readlane_b32 s12, v200, 3
	v_readlane_b32 s13, v200, 4
	v_readlane_b32 s14, v200, 5
	v_readlane_b32 s15, v200, 6
	v_readlane_b32 s16, v200, 7
	v_readlane_b32 s17, v200, 8
	v_readlane_b32 s18, v200, 9
	v_readlane_b32 s19, v200, 10
	v_readlane_b32 s21, v200, 11
	v_readlane_b32 s22, v200, 12
	v_readlane_b32 s23, v200, 13
	v_readlane_b32 s26, v200, 14
	v_readlane_b32 s27, v200, 15
	v_readlane_b32 s28, v200, 16
	v_readlane_b32 s29, v200, 17
	v_readlane_b32 s33, v200, 18
	v_readlane_b32 s34, v200, 19
	v_readlane_b32 s35, v200, 20
	v_readlane_b32 s36, v200, 21
	v_readlane_b32 s37, v200, 22
	v_readlane_b32 s43, v200, 23
	v_readlane_b32 s44, v200, 24
	v_readlane_b32 s45, v200, 25
	v_readlane_b32 s46, v200, 26
	v_readlane_b32 s47, v200, 27
	v_readlane_b32 s48, v200, 28
	v_readlane_b32 s49, v200, 29
	v_readlane_b32 s80, v200, 30
	v_readlane_b32 vcc_lo, v200, 31
	v_readlane_b32 vcc_hi, v200, 32
	s_nop 3
